# pool-GEMM residual epilogues: bias/scale vectors staged once per unit in LDS instead of 64 global loads each followed by vmcnt(0)
# speedup vs baseline: 1.0192x; 1.0017x over previous
; __device__ __forceinline__ unsigned pk2(float lo, float hi) { f32x2 v = {lo, hi}; bf16x2_t b = __builtin_convertvector(v, bf16x2_t); return __builtin_bit_cast(unsigned, b); }
; __device__ __forceinline__ float bflo(unsigned w) { return __uint_as_float(w << 16); }
; __device__ __forceinline__ float bfhi(unsigned w) { return __uint_as_float(w & 0xffff0000u); }
;     __device__ __forceinline__ void operator()(const f32x4 (&acc)[2][2][4][2], const Unit& u, int wr, int wc, int fr, int fq) const {
;         const int row0 = u.pm * BM + wr * 64 + fr, col0 = u.pn * BM + wc * 32 + 8 * fq;
;         u32x4 cur[2][2], nxt[2][2], nx2[2][2];
;         if (MODE < 3) { ldgrp(cur, (size_t)row0 * DM + col0); ldgrp(nxt, (size_t)(row0 + 16) * DM + col0); }
; #pragma unroll
;         for (int j = 0; j < 8; ++j) { const int ai = j >> 2, m = j & 3; const int row = row0 + ai * HALF + m * 16; const size_t off = (size_t)row * DM + col0; float ss = 0.f;
;             if (MODE < 3 && j < 6) ldgrp(nx2, (size_t)(row0 + ((j + 2) >> 2) * HALF + ((j + 2) & 3) * 16) * DM + col0);
; #pragma unroll
;             for (int bj = 0; bj < 2; ++bj) { f32x4 o[2];
; #pragma unroll
;                 for (int n = 0; n < 2; ++n) { const int cc = bj * HALF + 4 * n;
;                     f32x4 v = acc[ai][bj][m][n];
;                     if (bias) { v = (v + *(const f32x4*)(bias + col0 + cc)) * *(const f32x4*)(scale + col0 + cc); }
;                     f32x4 b;
;                     if (MODE >= 3) b = (f32x4){0.f, 0.f, 0.f, 0.f};
;                     else if (MODE == 0) b = __builtin_bit_cast(f32x4, cur[bj][n]);
;                     else { const unsigned w0 = n ? cur[bj][0].z : cur[bj][0].x, w1 = n ? cur[bj][0].w : cur[bj][0].y; b = (f32x4){bflo(w0), bfhi(w0), bflo(w1), bfhi(w1)}; }
;                     o[n] = b + v;
;                     if (MODE == 2 || MODE == 4) *(f32x4*)(out + off + cc) = o[n];
;                     ss += (o[n][0] * o[n][0] + o[n][1] * o[n][1]) + (o[n][2] * o[n][2] + o[n][3] * o[n][3]); }
;                 if (MODE != 2 && MODE != 4) { u32x4 w; w.x = pk2(o[0][0], o[0][1]); w.y = pk2(o[0][2], o[0][3]); w.z = pk2(o[1][0], o[1][1]); w.w = pk2(o[1][2], o[1][3]); *(u32x4*)(xb + off + bj * HALF) = w; } }
.LBB0_770:
	v_lshl_add_u32 v176, s52, 8, v185
	v_or_b32_e32 v178, 16, v176
	v_lshl_or_b32 v168, s10, 8, v187
	v_ashrrev_i32_e32 v177, 31, v176
	v_ashrrev_i32_e32 v179, 31, v178
	v_ashrrev_i32_e32 v169, 31, v168
	v_lshlrev_b64 v[122:123], 12, v[176:177]
	v_lshlrev_b64 v[124:125], 12, v[178:179]
	v_or_b32_e32 v172, 32, v176
	v_lshl_add_u64 v[170:171], s[60:61], 0, v[122:123]
	v_lshlrev_b64 v[122:123], 1, v[168:169]
	v_lshl_add_u64 v[124:125], s[60:61], 0, v[124:125]
	v_ashrrev_i32_e32 v173, 31, v172
	v_lshl_add_u64 v[180:181], v[124:125], 0, v[122:123]
	v_lshlrev_b64 v[124:125], 12, v[172:173]
	v_lshl_add_u64 v[124:125], s[60:61], 0, v[124:125]
	v_lshl_add_u64 v[182:183], v[170:171], 0, v[122:123]
	v_lshl_add_u64 v[174:175], v[124:125], 0, v[122:123]
	global_load_dwordx4 v[150:153], v[182:183], off
	global_load_dwordx4 v[146:149], v[182:183], off offset:256
	global_load_dwordx4 v[142:145], v[180:181], off
	global_load_dwordx4 v[138:141], v[180:181], off offset:256
	global_load_dwordx4 v[134:137], v[174:175], off
	global_load_dwordx4 v[122:125], v[174:175], off offset:256
	v_lshlrev_b64 v[164:165], 2, v[168:169]
	v_cndmask_b32_e64 v189, 0, 1, s[66:67]
	v_lshl_add_u64 v[166:167], s[14:15], 0, v[164:165]
	v_cmp_ne_u32_e64 s[8:9], 1, v189
	s_andn2_b64 vcc, exec, s[66:67]
	s_andn2_b64 vcc, exec, s[66:67]
	s_cbranch_vccnz .LpgA_nostage
	v_and_b32_e32 v228, 31, v251
	v_lshlrev_b32_e32 v228, 2, v228
	v_lshrrev_b32_e32 v229, 5, v251
	v_lshlrev_b32_e32 v234, 7, v229
	v_lshl_add_u32 v229, v229, 9, v228
	v_lshrrev_b32_e32 v232, 4, v251
	v_lshlrev_b32_e32 v232, 5, v232
	v_sub_u32_e32 v229, v229, v232
	v_add_u32_e32 v229, v164, v229
	v_lshrrev_b32_e32 v233, 7, v164
	v_and_b32_e32 v233, 3, v233
	v_lshlrev_b32_e32 v233, 9, v233
	v_add_u32_e32 v233, 0x20800, v233
	v_add_u32_e32 v203, v233, v232
	v_add3_u32 v234, v233, v234, v228
	v_mov_b32_e32 v231, s15
	v_add_co_u32_e32 v230, vcc, s14, v229
	s_nop 1
	v_addc_co_u32_e32 v231, vcc, 0, v231, vcc
	global_load_dword v232, v[230:231], off
	v_mov_b32_e32 v231, s35
	v_add_co_u32_e32 v230, vcc, s34, v229
	s_nop 1
	v_addc_co_u32_e32 v231, vcc, 0, v231, vcc
	global_load_dword v233, v[230:231], off
	s_waitcnt vmcnt(0)
	ds_write_b32 v234, v232
	ds_write_b32 v234, v233 offset:256
	s_waitcnt lgkmcnt(0)
.LpgA_nostage:
	s_andn2_b64 vcc, exec, s[66:67]
	v_lshl_add_u64 v[164:165], s[34:35], 0, v[164:165]
	s_cbranch_vccnz .LBB0_772
	ds_read_b128 v[190:193], v203
	s_waitcnt vmcnt(0) lgkmcnt(0)
	v_pk_add_f32 v[192:193], v[132:133], v[192:193]
	v_pk_add_f32 v[190:191], v[130:131], v[190:191]
	ds_read_b128 v[130:133], v203 offset:256
	s_waitcnt lgkmcnt(0)
	v_pk_mul_f32 v[132:133], v[192:193], v[132:133]
	v_pk_mul_f32 v[130:131], v[190:191], v[130:131]
.LBB0_772:
	s_and_b64 vcc, exec, s[8:9]
	s_cbranch_vccnz .LBB0_774
	ds_read_b128 v[190:193], v203 offset:16
	s_waitcnt lgkmcnt(0)
	v_pk_add_f32 v[192:193], v[128:129], v[192:193]
	v_pk_add_f32 v[190:191], v[126:127], v[190:191]
	ds_read_b128 v[126:129], v203 offset:272
	s_waitcnt lgkmcnt(0)
	v_pk_mul_f32 v[128:129], v[192:193], v[128:129]
	v_pk_mul_f32 v[126:127], v[190:191], v[126:127]
.LBB0_774:
	s_waitcnt vmcnt(0)
	v_lshlrev_b32_e32 v190, 16, v150
	v_and_b32_e32 v191, 0xffff0000, v150
	v_lshlrev_b32_e32 v150, 16, v151
	v_and_b32_e32 v151, 0xffff0000, v151
	v_pk_add_f32 v[132:133], v[132:133], v[150:151]
	v_lshlrev_b32_e32 v150, 16, v152
	v_and_b32_e32 v151, 0xffff0000, v152
	v_lshlrev_b32_e32 v152, 16, v153
	v_and_b32_e32 v153, 0xffff0000, v153
	v_pk_add_f32 v[130:131], v[130:131], v[190:191]
	v_pk_add_f32 v[128:129], v[128:129], v[152:153]
	v_pk_add_f32 v[126:127], v[126:127], v[150:151]
	v_cvt_pk_bf16_f32 v150, v130, v131
	v_cvt_pk_bf16_f32 v151, v132, v133
	v_cvt_pk_bf16_f32 v152, v126, v127
	v_cvt_pk_bf16_f32 v153, v128, v129
	s_and_b64 vcc, exec, s[8:9]
	global_store_dwordx4 v[182:183], v[150:153], off
	s_cbranch_vccnz .LBB0_776
	ds_read_b128 v[150:153], v203 offset:128
	s_waitcnt lgkmcnt(0)
	v_pk_add_f32 v[152:153], v[120:121], v[152:153]
	v_pk_add_f32 v[150:151], v[118:119], v[150:151]
	ds_read_b128 v[118:121], v203 offset:384
	s_waitcnt lgkmcnt(0)
	v_pk_mul_f32 v[120:121], v[152:153], v[120:121]
	v_pk_mul_f32 v[118:119], v[150:151], v[118:119]
.LBB0_776:
	s_and_b64 vcc, exec, s[8:9]
	s_cbranch_vccnz .LBB0_778
	ds_read_b128 v[150:153], v203 offset:144
	s_waitcnt lgkmcnt(0)
	v_pk_add_f32 v[152:153], v[116:117], v[152:153]
	v_pk_add_f32 v[150:151], v[114:115], v[150:151]
	ds_read_b128 v[114:117], v203 offset:400
	s_waitcnt lgkmcnt(0)
	v_pk_mul_f32 v[116:117], v[152:153], v[116:117]
	v_pk_mul_f32 v[114:115], v[150:151], v[114:115]

; __device__ __forceinline__ unsigned pk2(float lo, float hi) { f32x2 v = {lo, hi}; bf16x2_t b = __builtin_convertvector(v, bf16x2_t); return __builtin_bit_cast(unsigned, b); }
; __device__ __forceinline__ float bflo(unsigned w) { return __uint_as_float(w << 16); }
; __device__ __forceinline__ float bfhi(unsigned w) { return __uint_as_float(w & 0xffff0000u); }
;     __device__ __forceinline__ void operator()(const f32x4 (&acc)[2][2][4][2], const Unit& u, int wr, int wc, int fr, int fq) const {
;     ...
;         for (int j = 0; j < 8; ++j) { const int ai = j >> 2, m = j & 3; const int row = row0 + ai * HALF + m * 16; const size_t off = (size_t)row * DM + col0; float ss = 0.f;
;             if (MODE < 3 && j < 6) ldgrp(nx2, (size_t)(row0 + ((j + 2) >> 2) * HALF + ((j + 2) & 3) * 16) * DM + col0);
; #pragma unroll
;             for (int bj = 0; bj < 2; ++bj) { f32x4 o[2];
; #pragma unroll
;                 for (int n = 0; n < 2; ++n) { const int cc = bj * HALF + 4 * n;
;                     f32x4 v = acc[ai][bj][m][n];
;                     if (bias) { v = (v + *(const f32x4*)(bias + col0 + cc)) * *(const f32x4*)(scale + col0 + cc); }
;                     f32x4 b;
;                     if (MODE >= 3) b = (f32x4){0.f, 0.f, 0.f, 0.f};
;                     else if (MODE == 0) b = __builtin_bit_cast(f32x4, cur[bj][n]);
;                     else { const unsigned w0 = n ? cur[bj][0].z : cur[bj][0].x, w1 = n ? cur[bj][0].w : cur[bj][0].y; b = (f32x4){bflo(w0), bfhi(w0), bflo(w1), bfhi(w1)}; }
;                     o[n] = b + v;
;                     if (MODE == 2 || MODE == 4) *(f32x4*)(out + off + cc) = o[n];
;                     ss += (o[n][0] * o[n][0] + o[n][1] * o[n][1]) + (o[n][2] * o[n][2] + o[n][3] * o[n][3]); }
;                 if (MODE != 2 && MODE != 4) { u32x4 w; w.x = pk2(o[0][0], o[0][1]); w.y = pk2(o[0][2], o[0][3]); w.z = pk2(o[1][0], o[1][1]); w.w = pk2(o[1][2], o[1][3]); *(u32x4*)(xb + off + bj * HALF) = w; } }
;             if (MODE != 2 && MODE != 4 && rsq) { ss += __shfl_xor(ss, 16); ss += __shfl_xor(ss, 32); if (fq == 0) rsq[(size_t)row * 64 + u.pn * 4 + wc] = ss; }
.LBB0_782:
	v_or_b32_e32 v126, 48, v176
	v_ashrrev_i32_e32 v127, 31, v126
	s_waitcnt lgkmcnt(0)
	v_lshlrev_b64 v[114:115], 12, v[126:127]
	v_lshl_add_u64 v[114:115], s[60:61], 0, v[114:115]
	v_lshl_add_u64 v[128:129], v[168:169], 1, v[114:115]
	global_load_dwordx4 v[118:121], v[128:129], off
	global_load_dwordx4 v[114:117], v[128:129], off offset:256
	s_and_b64 vcc, exec, s[8:9]
	s_cbranch_vccnz .LBB0_784
	ds_read_b128 v[130:133], v203
	s_waitcnt vmcnt(2) lgkmcnt(0)
	v_pk_add_f32 v[132:133], v[112:113], v[132:133]
	v_pk_add_f32 v[130:131], v[110:111], v[130:131]
	ds_read_b128 v[110:113], v203 offset:256
	s_waitcnt lgkmcnt(0)
	v_pk_mul_f32 v[112:113], v[132:133], v[112:113]
	v_pk_mul_f32 v[110:111], v[130:131], v[110:111]
.LBB0_784:
	s_and_b64 vcc, exec, s[8:9]
	s_cbranch_vccnz .LBB0_786
	ds_read_b128 v[130:133], v203 offset:16
	s_waitcnt lgkmcnt(0)
	v_pk_add_f32 v[132:133], v[108:109], v[132:133]
	v_pk_add_f32 v[130:131], v[106:107], v[130:131]
	ds_read_b128 v[106:109], v203 offset:272
	s_waitcnt lgkmcnt(0)
	v_pk_mul_f32 v[108:109], v[132:133], v[108:109]
	v_pk_mul_f32 v[106:107], v[130:131], v[106:107]
.LBB0_786:
	v_lshlrev_b32_e32 v130, 16, v142
	v_and_b32_e32 v131, 0xffff0000, v142
	v_lshlrev_b32_e32 v132, 16, v143
	v_and_b32_e32 v133, 0xffff0000, v143
	v_pk_add_f32 v[112:113], v[112:113], v[132:133]
	v_pk_add_f32 v[110:111], v[110:111], v[130:131]
	v_lshlrev_b32_e32 v130, 16, v144
	v_and_b32_e32 v131, 0xffff0000, v144
	v_lshlrev_b32_e32 v132, 16, v145
	v_and_b32_e32 v133, 0xffff0000, v145
	v_pk_add_f32 v[108:109], v[108:109], v[132:133]
	v_pk_add_f32 v[106:107], v[106:107], v[130:131]
	v_cvt_pk_bf16_f32 v130, v110, v111
	v_cvt_pk_bf16_f32 v131, v112, v113
	v_cvt_pk_bf16_f32 v132, v106, v107
	v_cvt_pk_bf16_f32 v133, v108, v109
	s_and_b64 vcc, exec, s[8:9]
	global_store_dwordx4 v[180:181], v[130:133], off
	s_cbranch_vccnz .LBB0_788
	ds_read_b128 v[130:133], v203 offset:128
	s_waitcnt lgkmcnt(0)
	v_pk_add_f32 v[132:133], v[104:105], v[132:133]
	v_pk_add_f32 v[130:131], v[102:103], v[130:131]
	ds_read_b128 v[102:105], v203 offset:384
	s_waitcnt lgkmcnt(0)
	v_pk_mul_f32 v[104:105], v[132:133], v[104:105]
	v_pk_mul_f32 v[102:103], v[130:131], v[102:103]
.LBB0_788:
	s_and_b64 vcc, exec, s[8:9]
	s_cbranch_vccnz .LBB0_790
	ds_read_b128 v[130:133], v203 offset:144
	s_waitcnt lgkmcnt(0)
	v_pk_add_f32 v[132:133], v[100:101], v[132:133]
	v_pk_add_f32 v[130:131], v[98:99], v[130:131]
	ds_read_b128 v[98:101], v203 offset:400
	s_waitcnt lgkmcnt(0)
	v_pk_mul_f32 v[100:101], v[132:133], v[100:101]
	v_pk_mul_f32 v[98:99], v[130:131], v[98:99]

; __device__ __forceinline__ unsigned pk2(float lo, float hi) { f32x2 v = {lo, hi}; bf16x2_t b = __builtin_convertvector(v, bf16x2_t); return __builtin_bit_cast(unsigned, b); }
; __device__ __forceinline__ float bflo(unsigned w) { return __uint_as_float(w << 16); }
; __device__ __forceinline__ float bfhi(unsigned w) { return __uint_as_float(w & 0xffff0000u); }
;     __device__ __forceinline__ void operator()(const f32x4 (&acc)[2][2][4][2], const Unit& u, int wr, int wc, int fr, int fq) const {
;     ...
;         for (int j = 0; j < 8; ++j) { const int ai = j >> 2, m = j & 3; const int row = row0 + ai * HALF + m * 16; const size_t off = (size_t)row * DM + col0; float ss = 0.f;
;             if (MODE < 3 && j < 6) ldgrp(nx2, (size_t)(row0 + ((j + 2) >> 2) * HALF + ((j + 2) & 3) * 16) * DM + col0);
; #pragma unroll
;             for (int bj = 0; bj < 2; ++bj) { f32x4 o[2];
; #pragma unroll
;                 for (int n = 0; n < 2; ++n) { const int cc = bj * HALF + 4 * n;
;                     f32x4 v = acc[ai][bj][m][n];
;                     if (bias) { v = (v + *(const f32x4*)(bias + col0 + cc)) * *(const f32x4*)(scale + col0 + cc); }
;                     f32x4 b;
;                     if (MODE >= 3) b = (f32x4){0.f, 0.f, 0.f, 0.f};
;                     else if (MODE == 0) b = __builtin_bit_cast(f32x4, cur[bj][n]);
;                     else { const unsigned w0 = n ? cur[bj][0].z : cur[bj][0].x, w1 = n ? cur[bj][0].w : cur[bj][0].y; b = (f32x4){bflo(w0), bfhi(w0), bflo(w1), bfhi(w1)}; }
;                     o[n] = b + v;
;                     if (MODE == 2 || MODE == 4) *(f32x4*)(out + off + cc) = o[n];
;                     ss += (o[n][0] * o[n][0] + o[n][1] * o[n][1]) + (o[n][2] * o[n][2] + o[n][3] * o[n][3]); }
;                 if (MODE != 2 && MODE != 4) { u32x4 w; w.x = pk2(o[0][0], o[0][1]); w.y = pk2(o[0][2], o[0][3]); w.z = pk2(o[1][0], o[1][1]); w.w = pk2(o[1][2], o[1][3]); *(u32x4*)(xb + off + bj * HALF) = w; } }
;             if (MODE != 2 && MODE != 4 && rsq) { ss += __shfl_xor(ss, 16); ss += __shfl_xor(ss, 32); if (fq == 0) rsq[(size_t)row * 64 + u.pn * 4 + wc] = ss; }
.LBB0_794:
	v_add_u32_e32 v106, 0x80, v176
	v_ashrrev_i32_e32 v107, 31, v106
	s_waitcnt lgkmcnt(0)
	v_lshlrev_b64 v[98:99], 12, v[106:107]
	v_lshl_add_u64 v[98:99], s[60:61], 0, v[98:99]
	v_lshl_add_u64 v[108:109], v[168:169], 1, v[98:99]
	global_load_dwordx4 v[102:105], v[108:109], off
	global_load_dwordx4 v[98:101], v[108:109], off offset:256
	s_and_b64 vcc, exec, s[8:9]
	s_cbranch_vccnz .LBB0_796
	ds_read_b128 v[110:113], v203
	s_waitcnt vmcnt(2) lgkmcnt(0)
	v_pk_add_f32 v[112:113], v[94:95], v[112:113]
	v_pk_add_f32 v[110:111], v[92:93], v[110:111]
	ds_read_b128 v[92:95], v203 offset:256
	s_waitcnt lgkmcnt(0)
	v_pk_mul_f32 v[94:95], v[112:113], v[94:95]
	v_pk_mul_f32 v[92:93], v[110:111], v[92:93]
.LBB0_796:
	s_and_b64 vcc, exec, s[8:9]
	s_cbranch_vccnz .LBB0_798
	ds_read_b128 v[110:113], v203 offset:16
	s_waitcnt lgkmcnt(0)
	v_pk_add_f32 v[112:113], v[90:91], v[112:113]
	v_pk_add_f32 v[110:111], v[88:89], v[110:111]
	ds_read_b128 v[88:91], v203 offset:272
	s_waitcnt lgkmcnt(0)
	v_pk_mul_f32 v[90:91], v[112:113], v[90:91]
	v_pk_mul_f32 v[88:89], v[110:111], v[88:89]
.LBB0_798:
	v_lshlrev_b32_e32 v110, 16, v134
	v_and_b32_e32 v111, 0xffff0000, v134
	v_lshlrev_b32_e32 v112, 16, v135
	v_and_b32_e32 v113, 0xffff0000, v135
	v_pk_add_f32 v[94:95], v[94:95], v[112:113]
	v_pk_add_f32 v[92:93], v[92:93], v[110:111]
	v_lshlrev_b32_e32 v110, 16, v136
	v_and_b32_e32 v111, 0xffff0000, v136
	v_lshlrev_b32_e32 v112, 16, v137
	v_and_b32_e32 v113, 0xffff0000, v137
	v_pk_add_f32 v[90:91], v[90:91], v[112:113]
	v_pk_add_f32 v[88:89], v[88:89], v[110:111]
	v_cvt_pk_bf16_f32 v110, v92, v93
	v_cvt_pk_bf16_f32 v111, v94, v95
	v_cvt_pk_bf16_f32 v112, v88, v89
	v_cvt_pk_bf16_f32 v113, v90, v91
	s_and_b64 vcc, exec, s[8:9]
	global_store_dwordx4 v[174:175], v[110:113], off
	s_cbranch_vccnz .LBB0_800
	ds_read_b128 v[110:113], v203 offset:128
	s_waitcnt lgkmcnt(0)
	v_pk_add_f32 v[112:113], v[86:87], v[112:113]
	v_pk_add_f32 v[110:111], v[84:85], v[110:111]
	ds_read_b128 v[84:87], v203 offset:384
	s_waitcnt lgkmcnt(0)
	v_pk_mul_f32 v[86:87], v[112:113], v[86:87]
	v_pk_mul_f32 v[84:85], v[110:111], v[84:85]
.LBB0_800:
	s_and_b64 vcc, exec, s[8:9]
	s_cbranch_vccnz .LBB0_802
	ds_read_b128 v[110:113], v203 offset:144
	s_waitcnt lgkmcnt(0)
	v_pk_add_f32 v[112:113], v[82:83], v[112:113]
	v_pk_add_f32 v[110:111], v[80:81], v[110:111]
	ds_read_b128 v[80:83], v203 offset:400
	s_waitcnt lgkmcnt(0)
	v_pk_mul_f32 v[82:83], v[112:113], v[82:83]
	v_pk_mul_f32 v[80:81], v[110:111], v[80:81]

; __device__ __forceinline__ unsigned pk2(float lo, float hi) { f32x2 v = {lo, hi}; bf16x2_t b = __builtin_convertvector(v, bf16x2_t); return __builtin_bit_cast(unsigned, b); }
; __device__ __forceinline__ float bflo(unsigned w) { return __uint_as_float(w << 16); }
; __device__ __forceinline__ float bfhi(unsigned w) { return __uint_as_float(w & 0xffff0000u); }
;     __device__ __forceinline__ void operator()(const f32x4 (&acc)[2][2][4][2], const Unit& u, int wr, int wc, int fr, int fq) const {
;     ...
;         for (int j = 0; j < 8; ++j) { const int ai = j >> 2, m = j & 3; const int row = row0 + ai * HALF + m * 16; const size_t off = (size_t)row * DM + col0; float ss = 0.f;
;             if (MODE < 3 && j < 6) ldgrp(nx2, (size_t)(row0 + ((j + 2) >> 2) * HALF + ((j + 2) & 3) * 16) * DM + col0);
; #pragma unroll
;             for (int bj = 0; bj < 2; ++bj) { f32x4 o[2];
; #pragma unroll
;                 for (int n = 0; n < 2; ++n) { const int cc = bj * HALF + 4 * n;
;                     f32x4 v = acc[ai][bj][m][n];
;                     if (bias) { v = (v + *(const f32x4*)(bias + col0 + cc)) * *(const f32x4*)(scale + col0 + cc); }
;                     f32x4 b;
;                     if (MODE >= 3) b = (f32x4){0.f, 0.f, 0.f, 0.f};
;                     else if (MODE == 0) b = __builtin_bit_cast(f32x4, cur[bj][n]);
;                     else { const unsigned w0 = n ? cur[bj][0].z : cur[bj][0].x, w1 = n ? cur[bj][0].w : cur[bj][0].y; b = (f32x4){bflo(w0), bfhi(w0), bflo(w1), bfhi(w1)}; }
;                     o[n] = b + v;
;                     if (MODE == 2 || MODE == 4) *(f32x4*)(out + off + cc) = o[n];
;                     ss += (o[n][0] * o[n][0] + o[n][1] * o[n][1]) + (o[n][2] * o[n][2] + o[n][3] * o[n][3]); }
;                 if (MODE != 2 && MODE != 4) { u32x4 w; w.x = pk2(o[0][0], o[0][1]); w.y = pk2(o[0][2], o[0][3]); w.z = pk2(o[1][0], o[1][1]); w.w = pk2(o[1][2], o[1][3]); *(u32x4*)(xb + off + bj * HALF) = w; } }
;             if (MODE != 2 && MODE != 4 && rsq) { ss += __shfl_xor(ss, 16); ss += __shfl_xor(ss, 32); if (fq == 0) rsq[(size_t)row * 64 + u.pn * 4 + wc] = ss; }
.LBB0_806:
	s_waitcnt lgkmcnt(0)
	v_lshl_add_u64 v[80:81], v[168:169], 1, v[170:171]
	s_mov_b64 s[16:17], 0x90000
	v_lshl_add_u64 v[88:89], v[80:81], 0, s[16:17]
	v_add_co_u32_e32 v80, vcc, 0x90000, v80
	s_nop 1
	v_addc_co_u32_e32 v81, vcc, 0, v81, vcc
	global_load_dwordx4 v[84:87], v[80:81], off
	s_nop 0
	global_load_dwordx4 v[80:83], v[88:89], off offset:256
	s_and_b64 vcc, exec, s[8:9]
	s_cbranch_vccnz .LBB0_808
	ds_read_b128 v[90:93], v203
	s_waitcnt vmcnt(2) lgkmcnt(0)
	v_pk_add_f32 v[92:93], v[78:79], v[92:93]
	v_pk_add_f32 v[90:91], v[76:77], v[90:91]
	ds_read_b128 v[76:79], v203 offset:256
	s_waitcnt lgkmcnt(0)
	v_pk_mul_f32 v[78:79], v[92:93], v[78:79]
	v_pk_mul_f32 v[76:77], v[90:91], v[76:77]
.LBB0_808:
	s_and_b64 vcc, exec, s[8:9]
	s_cbranch_vccnz .LBB0_810
	ds_read_b128 v[90:93], v203 offset:16
	s_waitcnt lgkmcnt(0)
	v_pk_add_f32 v[92:93], v[74:75], v[92:93]
	v_pk_add_f32 v[90:91], v[72:73], v[90:91]
	ds_read_b128 v[72:75], v203 offset:272
	s_waitcnt lgkmcnt(0)
	v_pk_mul_f32 v[74:75], v[92:93], v[74:75]
	v_pk_mul_f32 v[72:73], v[90:91], v[72:73]
.LBB0_810:
	s_waitcnt vmcnt(9)
	v_lshlrev_b32_e32 v90, 16, v118
	v_and_b32_e32 v91, 0xffff0000, v118
	v_lshlrev_b32_e32 v92, 16, v119
	v_and_b32_e32 v93, 0xffff0000, v119
	v_pk_add_f32 v[78:79], v[78:79], v[92:93]
	v_pk_add_f32 v[76:77], v[76:77], v[90:91]
	v_lshlrev_b32_e32 v90, 16, v120
	v_and_b32_e32 v91, 0xffff0000, v120
	v_lshlrev_b32_e32 v92, 16, v121
	v_and_b32_e32 v93, 0xffff0000, v121
	v_pk_add_f32 v[74:75], v[74:75], v[92:93]
	v_pk_add_f32 v[72:73], v[72:73], v[90:91]
	v_cvt_pk_bf16_f32 v90, v76, v77
	v_cvt_pk_bf16_f32 v91, v78, v79
	v_cvt_pk_bf16_f32 v92, v72, v73
	v_cvt_pk_bf16_f32 v93, v74, v75
	s_and_b64 vcc, exec, s[8:9]
	global_store_dwordx4 v[128:129], v[90:93], off
	s_cbranch_vccnz .LBB0_812
	ds_read_b128 v[90:93], v203 offset:128
	s_waitcnt lgkmcnt(0)
	v_pk_add_f32 v[92:93], v[70:71], v[92:93]
	v_pk_add_f32 v[90:91], v[68:69], v[90:91]
	ds_read_b128 v[68:71], v203 offset:384
	s_waitcnt lgkmcnt(0)
	v_pk_mul_f32 v[70:71], v[92:93], v[70:71]
	v_pk_mul_f32 v[68:69], v[90:91], v[68:69]
.LBB0_812:
	s_and_b64 vcc, exec, s[8:9]
	s_cbranch_vccnz .LBB0_814
	ds_read_b128 v[90:93], v203 offset:144
	s_waitcnt lgkmcnt(0)
	v_pk_add_f32 v[92:93], v[66:67], v[92:93]
	v_pk_add_f32 v[90:91], v[64:65], v[90:91]
	ds_read_b128 v[64:67], v203 offset:400
	s_waitcnt lgkmcnt(0)
	v_pk_mul_f32 v[66:67], v[92:93], v[66:67]
	v_pk_mul_f32 v[64:65], v[90:91], v[64:65]

; __device__ __forceinline__ unsigned pk2(float lo, float hi) { f32x2 v = {lo, hi}; bf16x2_t b = __builtin_convertvector(v, bf16x2_t); return __builtin_bit_cast(unsigned, b); }
; __device__ __forceinline__ float bflo(unsigned w) { return __uint_as_float(w << 16); }
; __device__ __forceinline__ float bfhi(unsigned w) { return __uint_as_float(w & 0xffff0000u); }
;     __device__ __forceinline__ void operator()(const f32x4 (&acc)[2][2][4][2], const Unit& u, int wr, int wc, int fr, int fq) const {
;     ...
;         for (int j = 0; j < 8; ++j) { const int ai = j >> 2, m = j & 3; const int row = row0 + ai * HALF + m * 16; const size_t off = (size_t)row * DM + col0; float ss = 0.f;
;             if (MODE < 3 && j < 6) ldgrp(nx2, (size_t)(row0 + ((j + 2) >> 2) * HALF + ((j + 2) & 3) * 16) * DM + col0);
; #pragma unroll
;             for (int bj = 0; bj < 2; ++bj) { f32x4 o[2];
; #pragma unroll
;                 for (int n = 0; n < 2; ++n) { const int cc = bj * HALF + 4 * n;
;                     f32x4 v = acc[ai][bj][m][n];
;                     if (bias) { v = (v + *(const f32x4*)(bias + col0 + cc)) * *(const f32x4*)(scale + col0 + cc); }
;                     f32x4 b;
;                     if (MODE >= 3) b = (f32x4){0.f, 0.f, 0.f, 0.f};
;                     else if (MODE == 0) b = __builtin_bit_cast(f32x4, cur[bj][n]);
;                     else { const unsigned w0 = n ? cur[bj][0].z : cur[bj][0].x, w1 = n ? cur[bj][0].w : cur[bj][0].y; b = (f32x4){bflo(w0), bfhi(w0), bflo(w1), bfhi(w1)}; }
;                     o[n] = b + v;
;                     if (MODE == 2 || MODE == 4) *(f32x4*)(out + off + cc) = o[n];
;                     ss += (o[n][0] * o[n][0] + o[n][1] * o[n][1]) + (o[n][2] * o[n][2] + o[n][3] * o[n][3]); }
;                 if (MODE != 2 && MODE != 4) { u32x4 w; w.x = pk2(o[0][0], o[0][1]); w.y = pk2(o[0][2], o[0][3]); w.z = pk2(o[1][0], o[1][1]); w.w = pk2(o[1][2], o[1][3]); *(u32x4*)(xb + off + bj * HALF) = w; } }
;             if (MODE != 2 && MODE != 4 && rsq) { ss += __shfl_xor(ss, 16); ss += __shfl_xor(ss, 32); if (fq == 0) rsq[(size_t)row * 64 + u.pn * 4 + wc] = ss; }
.LBB0_818:
	v_or_b32_e32 v72, 32, v106
	v_ashrrev_i32_e32 v73, 31, v72
	s_waitcnt lgkmcnt(0)
	v_lshlrev_b64 v[64:65], 12, v[72:73]
	v_lshl_add_u64 v[64:65], s[60:61], 0, v[64:65]
	v_lshl_add_u64 v[74:75], v[168:169], 1, v[64:65]
	global_load_dwordx4 v[68:71], v[74:75], off
	global_load_dwordx4 v[64:67], v[74:75], off offset:256
	s_and_b64 vcc, exec, s[8:9]
	s_cbranch_vccnz .LBB0_820
	ds_read_b128 v[76:79], v203
	s_waitcnt vmcnt(2) lgkmcnt(0)
	v_pk_add_f32 v[78:79], v[62:63], v[78:79]
	v_pk_add_f32 v[76:77], v[60:61], v[76:77]
	ds_read_b128 v[60:63], v203 offset:256
	s_waitcnt lgkmcnt(0)
	v_pk_mul_f32 v[62:63], v[78:79], v[62:63]
	v_pk_mul_f32 v[60:61], v[76:77], v[60:61]
.LBB0_820:
	s_and_b64 vcc, exec, s[8:9]
	s_cbranch_vccnz .LBB0_822
	ds_read_b128 v[76:79], v203 offset:16
	s_waitcnt lgkmcnt(0)
	v_pk_add_f32 v[78:79], v[58:59], v[78:79]
	v_pk_add_f32 v[76:77], v[56:57], v[76:77]
	ds_read_b128 v[56:59], v203 offset:272
	s_waitcnt lgkmcnt(0)
	v_pk_mul_f32 v[58:59], v[78:79], v[58:59]
	v_pk_mul_f32 v[56:57], v[76:77], v[56:57]
.LBB0_822:
	s_waitcnt vmcnt(9)
	v_lshlrev_b32_e32 v76, 16, v102
	v_and_b32_e32 v77, 0xffff0000, v102
	v_lshlrev_b32_e32 v78, 16, v103
	v_and_b32_e32 v79, 0xffff0000, v103
	v_pk_add_f32 v[62:63], v[62:63], v[78:79]
	v_pk_add_f32 v[60:61], v[60:61], v[76:77]
	v_lshlrev_b32_e32 v76, 16, v104
	v_and_b32_e32 v77, 0xffff0000, v104
	v_lshlrev_b32_e32 v78, 16, v105
	v_and_b32_e32 v79, 0xffff0000, v105
	v_pk_add_f32 v[58:59], v[58:59], v[78:79]
	v_pk_add_f32 v[56:57], v[56:57], v[76:77]
	v_cvt_pk_bf16_f32 v76, v60, v61
	v_cvt_pk_bf16_f32 v77, v62, v63
	v_cvt_pk_bf16_f32 v78, v56, v57
	v_cvt_pk_bf16_f32 v79, v58, v59
	s_and_b64 vcc, exec, s[8:9]
	global_store_dwordx4 v[108:109], v[76:79], off
	s_cbranch_vccnz .LBB0_824
	ds_read_b128 v[76:79], v203 offset:128
	s_waitcnt lgkmcnt(0)
	v_pk_add_f32 v[78:79], v[54:55], v[78:79]
	v_pk_add_f32 v[76:77], v[52:53], v[76:77]
	ds_read_b128 v[52:55], v203 offset:384
	s_waitcnt lgkmcnt(0)
	v_pk_mul_f32 v[54:55], v[78:79], v[54:55]
	v_pk_mul_f32 v[52:53], v[76:77], v[52:53]
.LBB0_824:
	s_and_b64 vcc, exec, s[8:9]
	s_cbranch_vccnz .LBB0_826
	ds_read_b128 v[76:79], v203 offset:144
	s_waitcnt lgkmcnt(0)
	v_pk_add_f32 v[78:79], v[50:51], v[78:79]
	v_pk_add_f32 v[76:77], v[48:49], v[76:77]
	ds_read_b128 v[48:51], v203 offset:400
	s_waitcnt lgkmcnt(0)
	v_pk_mul_f32 v[50:51], v[78:79], v[50:51]
	v_pk_mul_f32 v[48:49], v[76:77], v[48:49]

; __device__ __forceinline__ unsigned pk2(float lo, float hi) { f32x2 v = {lo, hi}; bf16x2_t b = __builtin_convertvector(v, bf16x2_t); return __builtin_bit_cast(unsigned, b); }
; __device__ __forceinline__ float bflo(unsigned w) { return __uint_as_float(w << 16); }
; __device__ __forceinline__ float bfhi(unsigned w) { return __uint_as_float(w & 0xffff0000u); }
;     __device__ __forceinline__ void operator()(const f32x4 (&acc)[2][2][4][2], const Unit& u, int wr, int wc, int fr, int fq) const {
;     ...
;         for (int j = 0; j < 8; ++j) { const int ai = j >> 2, m = j & 3; const int row = row0 + ai * HALF + m * 16; const size_t off = (size_t)row * DM + col0; float ss = 0.f;
;             if (MODE < 3 && j < 6) ldgrp(nx2, (size_t)(row0 + ((j + 2) >> 2) * HALF + ((j + 2) & 3) * 16) * DM + col0);
; #pragma unroll
;             for (int bj = 0; bj < 2; ++bj) { f32x4 o[2];
; #pragma unroll
;                 for (int n = 0; n < 2; ++n) { const int cc = bj * HALF + 4 * n;
;                     f32x4 v = acc[ai][bj][m][n];
;                     if (bias) { v = (v + *(const f32x4*)(bias + col0 + cc)) * *(const f32x4*)(scale + col0 + cc); }
;                     f32x4 b;
;                     if (MODE >= 3) b = (f32x4){0.f, 0.f, 0.f, 0.f};
;                     else if (MODE == 0) b = __builtin_bit_cast(f32x4, cur[bj][n]);
;                     else { const unsigned w0 = n ? cur[bj][0].z : cur[bj][0].x, w1 = n ? cur[bj][0].w : cur[bj][0].y; b = (f32x4){bflo(w0), bfhi(w0), bflo(w1), bfhi(w1)}; }
;                     o[n] = b + v;
;                     if (MODE == 2 || MODE == 4) *(f32x4*)(out + off + cc) = o[n];
;                     ss += (o[n][0] * o[n][0] + o[n][1] * o[n][1]) + (o[n][2] * o[n][2] + o[n][3] * o[n][3]); }
;                 if (MODE != 2 && MODE != 4) { u32x4 w; w.x = pk2(o[0][0], o[0][1]); w.y = pk2(o[0][2], o[0][3]); w.z = pk2(o[1][0], o[1][1]); w.w = pk2(o[1][2], o[1][3]); *(u32x4*)(xb + off + bj * HALF) = w; } }
;             if (MODE != 2 && MODE != 4 && rsq) { ss += __shfl_xor(ss, 16); ss += __shfl_xor(ss, 32); if (fq == 0) rsq[(size_t)row * 64 + u.pn * 4 + wc] = ss; }
.LBB0_830:
	v_or_b32_e32 v56, 48, v106
	v_ashrrev_i32_e32 v57, 31, v56
	s_waitcnt lgkmcnt(0)
	v_lshlrev_b64 v[48:49], 12, v[56:57]
	v_lshl_add_u64 v[48:49], s[60:61], 0, v[48:49]
	v_lshl_add_u64 v[58:59], v[168:169], 1, v[48:49]
	global_load_dwordx4 v[52:55], v[58:59], off
	global_load_dwordx4 v[48:51], v[58:59], off offset:256
	s_and_b64 vcc, exec, s[8:9]
	s_cbranch_vccnz .LBB0_832
	ds_read_b128 v[60:63], v203
	s_waitcnt vmcnt(2) lgkmcnt(0)
	v_pk_add_f32 v[62:63], v[46:47], v[62:63]
	v_pk_add_f32 v[60:61], v[44:45], v[60:61]
	ds_read_b128 v[44:47], v203 offset:256
	s_waitcnt lgkmcnt(0)
	v_pk_mul_f32 v[46:47], v[62:63], v[46:47]
	v_pk_mul_f32 v[44:45], v[60:61], v[44:45]
.LBB0_832:
	s_and_b64 vcc, exec, s[8:9]
	s_cbranch_vccnz .LBB0_834
	ds_read_b128 v[60:63], v203 offset:16
	s_waitcnt lgkmcnt(0)
	v_pk_add_f32 v[62:63], v[42:43], v[62:63]
	v_pk_add_f32 v[60:61], v[40:41], v[60:61]
	ds_read_b128 v[40:43], v203 offset:272
	s_waitcnt lgkmcnt(0)
	v_pk_mul_f32 v[42:43], v[62:63], v[42:43]
	v_pk_mul_f32 v[40:41], v[60:61], v[40:41]
.LBB0_834:
	s_waitcnt vmcnt(9)
	v_lshlrev_b32_e32 v60, 16, v84
	v_and_b32_e32 v61, 0xffff0000, v84
	v_lshlrev_b32_e32 v62, 16, v85
	v_and_b32_e32 v63, 0xffff0000, v85
	v_pk_add_f32 v[46:47], v[46:47], v[62:63]
	v_pk_add_f32 v[44:45], v[44:45], v[60:61]
	v_lshlrev_b32_e32 v60, 16, v86
	v_and_b32_e32 v61, 0xffff0000, v86
	v_lshlrev_b32_e32 v62, 16, v87
	v_and_b32_e32 v63, 0xffff0000, v87
	v_pk_add_f32 v[42:43], v[42:43], v[62:63]
	v_pk_add_f32 v[40:41], v[40:41], v[60:61]
	v_cvt_pk_bf16_f32 v60, v44, v45
	v_cvt_pk_bf16_f32 v61, v46, v47
	v_cvt_pk_bf16_f32 v62, v40, v41
	v_cvt_pk_bf16_f32 v63, v42, v43
	s_and_b64 vcc, exec, s[8:9]
	global_store_dwordx4 v[88:89], v[60:63], off
	s_cbranch_vccnz .LBB0_836
	ds_read_b128 v[60:63], v203 offset:128
	s_waitcnt lgkmcnt(0)
	v_pk_add_f32 v[62:63], v[38:39], v[62:63]
	v_pk_add_f32 v[60:61], v[36:37], v[60:61]
	ds_read_b128 v[36:39], v203 offset:384
	s_waitcnt lgkmcnt(0)
	v_pk_mul_f32 v[38:39], v[62:63], v[38:39]
	v_pk_mul_f32 v[36:37], v[60:61], v[36:37]
.LBB0_836:
	s_and_b64 vcc, exec, s[8:9]
	s_cbranch_vccnz .LBB0_838
	ds_read_b128 v[60:63], v203 offset:144
	s_waitcnt lgkmcnt(0)
	v_pk_add_f32 v[62:63], v[34:35], v[62:63]
	v_pk_add_f32 v[60:61], v[32:33], v[60:61]
	ds_read_b128 v[32:35], v203 offset:400
	s_waitcnt lgkmcnt(0)
	v_pk_mul_f32 v[34:35], v[62:63], v[34:35]
	v_pk_mul_f32 v[32:33], v[60:61], v[32:33]

; __device__ __forceinline__ unsigned pk2(float lo, float hi) { f32x2 v = {lo, hi}; bf16x2_t b = __builtin_convertvector(v, bf16x2_t); return __builtin_bit_cast(unsigned, b); }
; __device__ __forceinline__ float bflo(unsigned w) { return __uint_as_float(w << 16); }
; __device__ __forceinline__ float bfhi(unsigned w) { return __uint_as_float(w & 0xffff0000u); }
;     __device__ __forceinline__ void operator()(const f32x4 (&acc)[2][2][4][2], const Unit& u, int wr, int wc, int fr, int fq) const {
;     ...
;         for (int j = 0; j < 8; ++j) { const int ai = j >> 2, m = j & 3; const int row = row0 + ai * HALF + m * 16; const size_t off = (size_t)row * DM + col0; float ss = 0.f;
;             if (MODE < 3 && j < 6) ldgrp(nx2, (size_t)(row0 + ((j + 2) >> 2) * HALF + ((j + 2) & 3) * 16) * DM + col0);
; #pragma unroll
;             for (int bj = 0; bj < 2; ++bj) { f32x4 o[2];
; #pragma unroll
;                 for (int n = 0; n < 2; ++n) { const int cc = bj * HALF + 4 * n;
;                     f32x4 v = acc[ai][bj][m][n];
;                     if (bias) { v = (v + *(const f32x4*)(bias + col0 + cc)) * *(const f32x4*)(scale + col0 + cc); }
;                     f32x4 b;
;                     if (MODE >= 3) b = (f32x4){0.f, 0.f, 0.f, 0.f};
;                     else if (MODE == 0) b = __builtin_bit_cast(f32x4, cur[bj][n]);
;                     else { const unsigned w0 = n ? cur[bj][0].z : cur[bj][0].x, w1 = n ? cur[bj][0].w : cur[bj][0].y; b = (f32x4){bflo(w0), bfhi(w0), bflo(w1), bfhi(w1)}; }
;                     o[n] = b + v;
;                     if (MODE == 2 || MODE == 4) *(f32x4*)(out + off + cc) = o[n];
;                     ss += (o[n][0] * o[n][0] + o[n][1] * o[n][1]) + (o[n][2] * o[n][2] + o[n][3] * o[n][3]); }
;                 if (MODE != 2 && MODE != 4) { u32x4 w; w.x = pk2(o[0][0], o[0][1]); w.y = pk2(o[0][2], o[0][3]); w.z = pk2(o[1][0], o[1][1]); w.w = pk2(o[1][2], o[1][3]); *(u32x4*)(xb + off + bj * HALF) = w; } }
;             if (MODE != 2 && MODE != 4 && rsq) { ss += __shfl_xor(ss, 16); ss += __shfl_xor(ss, 32); if (fq == 0) rsq[(size_t)row * 64 + u.pn * 4 + wc] = ss; }
.LBB0_842:
	s_and_b64 vcc, exec, s[8:9]
	s_cbranch_vccnz .LBB0_844
	s_waitcnt lgkmcnt(0)
	ds_read_b128 v[32:35], v203
	s_waitcnt vmcnt(0) lgkmcnt(0)
	v_pk_add_f32 v[34:35], v[30:31], v[34:35]
	v_pk_add_f32 v[32:33], v[28:29], v[32:33]
	ds_read_b128 v[28:31], v203 offset:256
	s_waitcnt lgkmcnt(0)
	v_pk_mul_f32 v[30:31], v[34:35], v[30:31]
	v_pk_mul_f32 v[28:29], v[32:33], v[28:29]
.LBB0_844:
	s_and_b64 vcc, exec, s[8:9]
	s_cbranch_vccnz .LBB0_846
	s_waitcnt lgkmcnt(0)
	ds_read_b128 v[32:35], v203 offset:16
	s_waitcnt lgkmcnt(0)
	v_pk_add_f32 v[34:35], v[26:27], v[34:35]
	v_pk_add_f32 v[32:33], v[24:25], v[32:33]
	ds_read_b128 v[24:27], v203 offset:272
	s_waitcnt lgkmcnt(0)
	v_pk_mul_f32 v[26:27], v[34:35], v[26:27]
	v_pk_mul_f32 v[24:25], v[32:33], v[24:25]
.LBB0_846:
	s_waitcnt vmcnt(7)
	v_lshlrev_b32_e32 v32, 16, v68
	s_waitcnt lgkmcnt(0)
	v_and_b32_e32 v33, 0xffff0000, v68
	v_lshlrev_b32_e32 v34, 16, v69
	v_and_b32_e32 v35, 0xffff0000, v69
	v_pk_add_f32 v[30:31], v[30:31], v[34:35]
	v_pk_add_f32 v[28:29], v[28:29], v[32:33]
	v_lshlrev_b32_e32 v32, 16, v70
	v_and_b32_e32 v33, 0xffff0000, v70
	v_lshlrev_b32_e32 v34, 16, v71
	v_and_b32_e32 v35, 0xffff0000, v71
	v_pk_add_f32 v[26:27], v[26:27], v[34:35]
	v_pk_add_f32 v[24:25], v[24:25], v[32:33]
	v_cvt_pk_bf16_f32 v32, v28, v29
	v_cvt_pk_bf16_f32 v33, v30, v31
	v_cvt_pk_bf16_f32 v34, v24, v25
	v_cvt_pk_bf16_f32 v35, v26, v27
	s_and_b64 vcc, exec, s[8:9]
	global_store_dwordx4 v[74:75], v[32:35], off
	s_cbranch_vccnz .LBB0_848
	ds_read_b128 v[32:35], v203 offset:128
	s_waitcnt lgkmcnt(0)
	v_pk_add_f32 v[34:35], v[22:23], v[34:35]
	v_pk_add_f32 v[32:33], v[20:21], v[32:33]
	ds_read_b128 v[20:23], v203 offset:384
	s_waitcnt lgkmcnt(0)
	v_pk_mul_f32 v[22:23], v[34:35], v[22:23]
	v_pk_mul_f32 v[20:21], v[32:33], v[20:21]
.LBB0_848:
	s_and_b64 vcc, exec, s[8:9]
	s_cbranch_vccnz .LBB0_850
	ds_read_b128 v[32:35], v203 offset:144
	s_waitcnt lgkmcnt(0)
	v_pk_add_f32 v[34:35], v[18:19], v[34:35]
	v_pk_add_f32 v[32:33], v[16:17], v[32:33]
	ds_read_b128 v[16:19], v203 offset:400
	s_waitcnt lgkmcnt(0)
	v_pk_mul_f32 v[18:19], v[34:35], v[18:19]
	v_pk_mul_f32 v[16:17], v[32:33], v[16:17]

; __device__ __forceinline__ unsigned pk2(float lo, float hi) { f32x2 v = {lo, hi}; bf16x2_t b = __builtin_convertvector(v, bf16x2_t); return __builtin_bit_cast(unsigned, b); }
; __device__ __forceinline__ float bflo(unsigned w) { return __uint_as_float(w << 16); }
; __device__ __forceinline__ float bfhi(unsigned w) { return __uint_as_float(w & 0xffff0000u); }
;     __device__ __forceinline__ void operator()(const f32x4 (&acc)[2][2][4][2], const Unit& u, int wr, int wc, int fr, int fq) const {
;     ...
;         for (int j = 0; j < 8; ++j) { const int ai = j >> 2, m = j & 3; const int row = row0 + ai * HALF + m * 16; const size_t off = (size_t)row * DM + col0; float ss = 0.f;
;             if (MODE < 3 && j < 6) ldgrp(nx2, (size_t)(row0 + ((j + 2) >> 2) * HALF + ((j + 2) & 3) * 16) * DM + col0);
; #pragma unroll
;             for (int bj = 0; bj < 2; ++bj) { f32x4 o[2];
; #pragma unroll
;                 for (int n = 0; n < 2; ++n) { const int cc = bj * HALF + 4 * n;
;                     f32x4 v = acc[ai][bj][m][n];
;                     if (bias) { v = (v + *(const f32x4*)(bias + col0 + cc)) * *(const f32x4*)(scale + col0 + cc); }
;                     f32x4 b;
;                     if (MODE >= 3) b = (f32x4){0.f, 0.f, 0.f, 0.f};
;                     else if (MODE == 0) b = __builtin_bit_cast(f32x4, cur[bj][n]);
;                     else { const unsigned w0 = n ? cur[bj][0].z : cur[bj][0].x, w1 = n ? cur[bj][0].w : cur[bj][0].y; b = (f32x4){bflo(w0), bfhi(w0), bflo(w1), bfhi(w1)}; }
;                     o[n] = b + v;
;                     if (MODE == 2 || MODE == 4) *(f32x4*)(out + off + cc) = o[n];
;                     ss += (o[n][0] * o[n][0] + o[n][1] * o[n][1]) + (o[n][2] * o[n][2] + o[n][3] * o[n][3]); }
;                 if (MODE != 2 && MODE != 4) { u32x4 w; w.x = pk2(o[0][0], o[0][1]); w.y = pk2(o[0][2], o[0][3]); w.z = pk2(o[1][0], o[1][1]); w.w = pk2(o[1][2], o[1][3]); *(u32x4*)(xb + off + bj * HALF) = w; } }
;             if (MODE != 2 && MODE != 4 && rsq) { ss += __shfl_xor(ss, 16); ss += __shfl_xor(ss, 32); if (fq == 0) rsq[(size_t)row * 64 + u.pn * 4 + wc] = ss; }
.LBB0_854:
	s_and_b64 vcc, exec, s[8:9]
	s_cbranch_vccnz .LBB0_856
	s_waitcnt lgkmcnt(0)
	ds_read_b128 v[16:19], v203
	s_waitcnt vmcnt(0) lgkmcnt(0)
	v_pk_add_f32 v[18:19], v[14:15], v[18:19]
	v_pk_add_f32 v[16:17], v[12:13], v[16:17]
	ds_read_b128 v[12:15], v203 offset:256
	s_waitcnt lgkmcnt(0)
	v_pk_mul_f32 v[14:15], v[18:19], v[14:15]
	v_pk_mul_f32 v[12:13], v[16:17], v[12:13]
.LBB0_856:
	s_and_b64 vcc, exec, s[8:9]
	s_cbranch_vccnz .LBB0_858
	s_waitcnt lgkmcnt(0)
	ds_read_b128 v[16:19], v203 offset:16
	s_waitcnt lgkmcnt(0)
	v_pk_add_f32 v[18:19], v[10:11], v[18:19]
	v_pk_add_f32 v[16:17], v[8:9], v[16:17]
	ds_read_b128 v[8:11], v203 offset:272
	s_waitcnt lgkmcnt(0)
	v_pk_mul_f32 v[10:11], v[18:19], v[10:11]
	v_pk_mul_f32 v[8:9], v[16:17], v[8:9]
.LBB0_858:
	s_waitcnt vmcnt(5)
	v_lshlrev_b32_e32 v16, 16, v52
	s_waitcnt lgkmcnt(0)
	v_and_b32_e32 v17, 0xffff0000, v52
	v_lshlrev_b32_e32 v18, 16, v53
	v_and_b32_e32 v19, 0xffff0000, v53
	v_pk_add_f32 v[14:15], v[14:15], v[18:19]
	v_pk_add_f32 v[12:13], v[12:13], v[16:17]
	v_lshlrev_b32_e32 v16, 16, v54
	v_and_b32_e32 v17, 0xffff0000, v54
	v_lshlrev_b32_e32 v18, 16, v55
	v_and_b32_e32 v19, 0xffff0000, v55
	v_pk_add_f32 v[10:11], v[10:11], v[18:19]
	v_pk_add_f32 v[8:9], v[8:9], v[16:17]
	v_cvt_pk_bf16_f32 v16, v12, v13
	v_cvt_pk_bf16_f32 v17, v14, v15
	v_cvt_pk_bf16_f32 v18, v8, v9
	v_cvt_pk_bf16_f32 v19, v10, v11
	s_and_b64 vcc, exec, s[8:9]
	global_store_dwordx4 v[58:59], v[16:19], off
	s_cbranch_vccnz .LBB0_860
	ds_read_b128 v[16:19], v203 offset:128
	s_waitcnt lgkmcnt(0)
	v_pk_add_f32 v[18:19], v[6:7], v[18:19]
	v_pk_add_f32 v[16:17], v[4:5], v[16:17]
	ds_read_b128 v[4:7], v203 offset:384
	s_waitcnt lgkmcnt(0)
	v_pk_mul_f32 v[6:7], v[18:19], v[6:7]
	v_pk_mul_f32 v[4:5], v[16:17], v[4:5]
.LBB0_860:
	s_and_b64 vcc, exec, s[8:9]
	s_cbranch_vccnz .LBB0_862
	ds_read_b128 v[16:19], v203 offset:144
	s_waitcnt lgkmcnt(0)
	v_pk_add_f32 v[18:19], v[2:3], v[18:19]
	v_pk_add_f32 v[16:17], v[0:1], v[16:17]
	ds_read_b128 v[0:3], v203 offset:400
	s_waitcnt lgkmcnt(0)
	v_pk_mul_f32 v[2:3], v[18:19], v[2:3]
	v_pk_mul_f32 v[0:1], v[16:17], v[0:1]

; __device__ __forceinline__ unsigned pk2(float lo, float hi) { f32x2 v = {lo, hi}; bf16x2_t b = __builtin_convertvector(v, bf16x2_t); return __builtin_bit_cast(unsigned, b); }
; __device__ __forceinline__ float bflo(unsigned w) { return __uint_as_float(w << 16); }
; __device__ __forceinline__ float bfhi(unsigned w) { return __uint_as_float(w & 0xffff0000u); }
;     __device__ __forceinline__ void operator()(const f32x4 (&acc)[2][2][4][2], const Unit& u, int wr, int wc, int fr, int fq) const {
;         const int row0 = u.pm * BM + wr * 64 + fr, col0 = u.pn * BM + wc * 32 + 8 * fq;
;         u32x4 cur[2][2], nxt[2][2], nx2[2][2];
;         if (MODE < 3) { ldgrp(cur, (size_t)row0 * DM + col0); ldgrp(nxt, (size_t)(row0 + 16) * DM + col0); }
; #pragma unroll
;         for (int j = 0; j < 8; ++j) { const int ai = j >> 2, m = j & 3; const int row = row0 + ai * HALF + m * 16; const size_t off = (size_t)row * DM + col0; float ss = 0.f;
;             if (MODE < 3 && j < 6) ldgrp(nx2, (size_t)(row0 + ((j + 2) >> 2) * HALF + ((j + 2) & 3) * 16) * DM + col0);
; #pragma unroll
;             for (int bj = 0; bj < 2; ++bj) { f32x4 o[2];
; #pragma unroll
;                 for (int n = 0; n < 2; ++n) { const int cc = bj * HALF + 4 * n;
;                     f32x4 v = acc[ai][bj][m][n];
;                     if (bias) { v = (v + *(const f32x4*)(bias + col0 + cc)) * *(const f32x4*)(scale + col0 + cc); }
;                     f32x4 b;
;                     if (MODE >= 3) b = (f32x4){0.f, 0.f, 0.f, 0.f};
;                     else if (MODE == 0) b = __builtin_bit_cast(f32x4, cur[bj][n]);
;                     else { const unsigned w0 = n ? cur[bj][0].z : cur[bj][0].x, w1 = n ? cur[bj][0].w : cur[bj][0].y; b = (f32x4){bflo(w0), bfhi(w0), bflo(w1), bfhi(w1)}; }
;                     o[n] = b + v;
;                     if (MODE == 2 || MODE == 4) *(f32x4*)(out + off + cc) = o[n];
;                     ss += (o[n][0] * o[n][0] + o[n][1] * o[n][1]) + (o[n][2] * o[n][2] + o[n][3] * o[n][3]); }
;                 if (MODE != 2 && MODE != 4) { u32x4 w; w.x = pk2(o[0][0], o[0][1]); w.y = pk2(o[0][2], o[0][3]); w.z = pk2(o[1][0], o[1][1]); w.w = pk2(o[1][2], o[1][3]); *(u32x4*)(xb + off + bj * HALF) = w; } }
.LBB0_896:
	v_lshl_add_u32 v198, s52, 8, v210
	v_lshl_or_b32 v192, s10, 8, v212
	v_ashrrev_i32_e32 v199, 31, v198
	v_ashrrev_i32_e32 v193, 31, v192
	v_lshlrev_b64 v[122:123], 13, v[198:199]
	v_lshl_add_u64 v[194:195], s[12:13], 0, v[122:123]
	v_lshlrev_b64 v[188:189], 2, v[192:193]
	v_or_b32_e32 v200, 16, v198
	v_lshl_add_u64 v[122:123], v[194:195], 0, v[188:189]
	v_ashrrev_i32_e32 v201, 31, v200
	global_load_dwordx4 v[170:173], v[122:123], off offset:16
	global_load_dwordx4 v[174:177], v[122:123], off
	global_load_dwordx4 v[162:165], v[122:123], off offset:528
	global_load_dwordx4 v[166:169], v[122:123], off offset:512
	v_lshlrev_b64 v[122:123], 13, v[200:201]
	v_lshl_add_u64 v[122:123], s[12:13], 0, v[122:123]
	v_or_b32_e32 v196, 32, v198
	v_lshl_add_u64 v[122:123], v[122:123], 0, v[188:189]
	v_ashrrev_i32_e32 v197, 31, v196
	global_load_dwordx4 v[154:157], v[122:123], off offset:16
	global_load_dwordx4 v[158:161], v[122:123], off
	global_load_dwordx4 v[146:149], v[122:123], off offset:528
	global_load_dwordx4 v[150:153], v[122:123], off offset:512
	v_lshlrev_b64 v[122:123], 13, v[196:197]
	v_lshl_add_u64 v[122:123], s[12:13], 0, v[122:123]
	v_lshl_add_u64 v[130:131], v[122:123], 0, v[188:189]
	global_load_dwordx4 v[138:141], v[130:131], off offset:16
	global_load_dwordx4 v[142:145], v[130:131], off
	global_load_dwordx4 v[122:125], v[130:131], off offset:528
	s_nop 0
	global_load_dwordx4 v[130:133], v[130:131], off offset:512
	v_cndmask_b32_e64 v202, 0, 1, s[68:69]
	v_lshl_add_u64 v[190:191], s[14:15], 0, v[188:189]
	v_cmp_ne_u32_e64 s[8:9], 1, v202
	s_andn2_b64 vcc, exec, s[68:69]
	s_andn2_b64 vcc, exec, s[68:69]
	s_cbranch_vccnz .LpgB_nostage
	v_and_b32_e32 v228, 31, v251
	v_lshlrev_b32_e32 v228, 2, v228
	v_lshrrev_b32_e32 v229, 5, v251
	v_lshlrev_b32_e32 v234, 7, v229
	v_lshl_add_u32 v229, v229, 9, v228
	v_lshrrev_b32_e32 v232, 4, v251
	v_lshlrev_b32_e32 v232, 5, v232
	v_sub_u32_e32 v229, v229, v232
	v_add_u32_e32 v229, v188, v229
	v_lshrrev_b32_e32 v233, 7, v188
	v_and_b32_e32 v233, 3, v233
	v_lshlrev_b32_e32 v233, 9, v233
	v_add_u32_e32 v233, 0x20800, v233
	v_add_u32_e32 v203, v233, v232
	v_add3_u32 v234, v233, v234, v228
	v_mov_b32_e32 v231, s15
	v_add_co_u32_e32 v230, vcc, s14, v229
	s_nop 1
	v_addc_co_u32_e32 v231, vcc, 0, v231, vcc
	global_load_dword v232, v[230:231], off
	v_mov_b32_e32 v231, s35
	v_add_co_u32_e32 v230, vcc, s34, v229
	s_nop 1
	v_addc_co_u32_e32 v231, vcc, 0, v231, vcc
	global_load_dword v233, v[230:231], off
	s_waitcnt vmcnt(0)
	ds_write_b32 v234, v232
	ds_write_b32 v234, v233 offset:256
	s_waitcnt lgkmcnt(0)
.LpgB_nostage:
	s_andn2_b64 vcc, exec, s[68:69]
	v_lshl_add_u64 v[188:189], s[34:35], 0, v[188:189]
	s_cbranch_vccnz .LBB0_898
	ds_read_b128 v[214:217], v203
	s_waitcnt vmcnt(0) lgkmcnt(0)
	v_pk_add_f32 v[216:217], v[136:137], v[216:217]
	v_pk_add_f32 v[214:215], v[134:135], v[214:215]
	ds_read_b128 v[134:137], v203 offset:256
	s_waitcnt lgkmcnt(0)
	v_pk_mul_f32 v[136:137], v[216:217], v[136:137]
	v_pk_mul_f32 v[134:135], v[214:215], v[134:135]
.LBB0_898:
	s_and_b64 vcc, exec, s[8:9]
	s_cbranch_vccnz .LBB0_900
	ds_read_b128 v[214:217], v203 offset:16
	s_waitcnt lgkmcnt(0)
	v_pk_add_f32 v[216:217], v[128:129], v[216:217]
	v_pk_add_f32 v[214:215], v[126:127], v[214:215]
	ds_read_b128 v[126:129], v203 offset:272
	s_waitcnt lgkmcnt(0)
	v_pk_mul_f32 v[128:129], v[216:217], v[128:129]
	v_pk_mul_f32 v[126:127], v[214:215], v[126:127]
.LBB0_900:
	s_waitcnt vmcnt(0)
	v_pk_add_f32 v[136:137], v[176:177], v[136:137]
	v_lshlrev_b64 v[176:177], 12, v[198:199]
	v_pk_add_f32 v[134:135], v[174:175], v[134:135]
	v_pk_add_f32 v[128:129], v[172:173], v[128:129]
	v_pk_add_f32 v[126:127], v[170:171], v[126:127]
	v_lshl_add_u64 v[170:171], s[62:63], 0, v[176:177]
	v_cvt_pk_bf16_f32 v172, v134, v135
	v_cvt_pk_bf16_f32 v173, v136, v137
	v_cvt_pk_bf16_f32 v174, v126, v127
	v_cvt_pk_bf16_f32 v175, v128, v129
	v_lshl_add_u64 v[170:171], v[192:193], 1, v[170:171]
	s_and_b64 vcc, exec, s[8:9]
	global_store_dwordx4 v[170:171], v[172:175], off
	s_cbranch_vccnz .LBB0_902
	ds_read_b128 v[172:175], v203 offset:128
	s_waitcnt lgkmcnt(0)
	v_pk_add_f32 v[174:175], v[120:121], v[174:175]
	v_pk_add_f32 v[172:173], v[118:119], v[172:173]
	ds_read_b128 v[118:121], v203 offset:384
	s_waitcnt lgkmcnt(0)
	v_pk_mul_f32 v[120:121], v[174:175], v[120:121]
	v_pk_mul_f32 v[118:119], v[172:173], v[118:119]
.LBB0_902:
	s_and_b64 vcc, exec, s[8:9]
	s_cbranch_vccnz .LBB0_904
	ds_read_b128 v[172:175], v203 offset:144
	s_waitcnt lgkmcnt(0)
	v_pk_add_f32 v[174:175], v[116:117], v[174:175]
	v_pk_add_f32 v[172:173], v[114:115], v[172:173]
	ds_read_b128 v[114:117], v203 offset:400
	s_waitcnt lgkmcnt(0)
	v_pk_mul_f32 v[116:117], v[174:175], v[116:117]
	v_pk_mul_f32 v[114:115], v[172:173], v[114:115]

; __device__ __forceinline__ unsigned pk2(float lo, float hi) { f32x2 v = {lo, hi}; bf16x2_t b = __builtin_convertvector(v, bf16x2_t); return __builtin_bit_cast(unsigned, b); }
; __device__ __forceinline__ float bflo(unsigned w) { return __uint_as_float(w << 16); }
; __device__ __forceinline__ float bfhi(unsigned w) { return __uint_as_float(w & 0xffff0000u); }
;     __device__ __forceinline__ void operator()(const f32x4 (&acc)[2][2][4][2], const Unit& u, int wr, int wc, int fr, int fq) const {
;     ...
;         for (int j = 0; j < 8; ++j) { const int ai = j >> 2, m = j & 3; const int row = row0 + ai * HALF + m * 16; const size_t off = (size_t)row * DM + col0; float ss = 0.f;
;             if (MODE < 3 && j < 6) ldgrp(nx2, (size_t)(row0 + ((j + 2) >> 2) * HALF + ((j + 2) & 3) * 16) * DM + col0);
; #pragma unroll
;             for (int bj = 0; bj < 2; ++bj) { f32x4 o[2];
; #pragma unroll
;                 for (int n = 0; n < 2; ++n) { const int cc = bj * HALF + 4 * n;
;                     f32x4 v = acc[ai][bj][m][n];
;                     if (bias) { v = (v + *(const f32x4*)(bias + col0 + cc)) * *(const f32x4*)(scale + col0 + cc); }
;                     f32x4 b;
;                     if (MODE >= 3) b = (f32x4){0.f, 0.f, 0.f, 0.f};
;                     else if (MODE == 0) b = __builtin_bit_cast(f32x4, cur[bj][n]);
;                     else { const unsigned w0 = n ? cur[bj][0].z : cur[bj][0].x, w1 = n ? cur[bj][0].w : cur[bj][0].y; b = (f32x4){bflo(w0), bfhi(w0), bflo(w1), bfhi(w1)}; }
;                     o[n] = b + v;
;                     if (MODE == 2 || MODE == 4) *(f32x4*)(out + off + cc) = o[n];
;                     ss += (o[n][0] * o[n][0] + o[n][1] * o[n][1]) + (o[n][2] * o[n][2] + o[n][3] * o[n][3]); }
;                 if (MODE != 2 && MODE != 4) { u32x4 w; w.x = pk2(o[0][0], o[0][1]); w.y = pk2(o[0][2], o[0][3]); w.z = pk2(o[1][0], o[1][1]); w.w = pk2(o[1][2], o[1][3]); *(u32x4*)(xb + off + bj * HALF) = w; } }
;             if (MODE != 2 && MODE != 4 && rsq) { ss += __shfl_xor(ss, 16); ss += __shfl_xor(ss, 32); if (fq == 0) rsq[(size_t)row * 64 + u.pn * 4 + wc] = ss; }
.LBB0_908:
	s_nop 0
	v_or_b32_e32 v162, 48, v198
	v_ashrrev_i32_e32 v163, 31, v162
	s_waitcnt lgkmcnt(0)
	v_lshlrev_b64 v[114:115], 13, v[162:163]
	v_lshl_add_u64 v[114:115], s[12:13], 0, v[114:115]
	v_lshl_add_u64 v[118:119], v[192:193], 2, v[114:115]
	global_load_dwordx4 v[126:129], v[118:119], off offset:16
	global_load_dwordx4 v[134:137], v[118:119], off
	global_load_dwordx4 v[114:117], v[118:119], off offset:528
	s_nop 0
	global_load_dwordx4 v[118:121], v[118:119], off offset:512
	s_and_b64 vcc, exec, s[8:9]
	s_cbranch_vccnz .LBB0_910
	ds_read_b128 v[164:167], v203
	s_waitcnt vmcnt(4) lgkmcnt(0)
	v_pk_add_f32 v[166:167], v[112:113], v[166:167]
	v_pk_add_f32 v[164:165], v[110:111], v[164:165]
	ds_read_b128 v[110:113], v203 offset:256
	s_waitcnt lgkmcnt(0)
	v_pk_mul_f32 v[112:113], v[166:167], v[112:113]
	v_pk_mul_f32 v[110:111], v[164:165], v[110:111]
.LBB0_910:
	s_and_b64 vcc, exec, s[8:9]
	s_cbranch_vccnz .LBB0_912
	ds_read_b128 v[164:167], v203 offset:16
	s_waitcnt lgkmcnt(0)
	v_pk_add_f32 v[166:167], v[108:109], v[166:167]
	v_pk_add_f32 v[164:165], v[106:107], v[164:165]
	ds_read_b128 v[106:109], v203 offset:272
	s_waitcnt lgkmcnt(0)
	v_pk_mul_f32 v[108:109], v[166:167], v[108:109]
	v_pk_mul_f32 v[106:107], v[164:165], v[106:107]
.LBB0_912:
	v_pk_add_f32 v[112:113], v[160:161], v[112:113]
	v_lshlrev_b64 v[160:161], 12, v[200:201]
	v_pk_add_f32 v[110:111], v[158:159], v[110:111]
	v_pk_add_f32 v[108:109], v[156:157], v[108:109]
	v_pk_add_f32 v[106:107], v[154:155], v[106:107]
	v_lshl_add_u64 v[154:155], s[62:63], 0, v[160:161]
	v_cvt_pk_bf16_f32 v156, v110, v111
	v_cvt_pk_bf16_f32 v157, v112, v113
	v_cvt_pk_bf16_f32 v158, v106, v107
	v_cvt_pk_bf16_f32 v159, v108, v109
	v_lshl_add_u64 v[154:155], v[192:193], 1, v[154:155]
	s_and_b64 vcc, exec, s[8:9]
	global_store_dwordx4 v[154:155], v[156:159], off
	s_cbranch_vccnz .LBB0_914
	ds_read_b128 v[156:159], v203 offset:128
	s_waitcnt lgkmcnt(0)
	v_pk_add_f32 v[158:159], v[104:105], v[158:159]
	v_pk_add_f32 v[156:157], v[102:103], v[156:157]
	ds_read_b128 v[102:105], v203 offset:384
	s_waitcnt lgkmcnt(0)
	v_pk_mul_f32 v[104:105], v[158:159], v[104:105]
	v_pk_mul_f32 v[102:103], v[156:157], v[102:103]
.LBB0_914:
	s_and_b64 vcc, exec, s[8:9]
	s_cbranch_vccnz .LBB0_916
	ds_read_b128 v[156:159], v203 offset:144
	s_waitcnt lgkmcnt(0)
	v_pk_add_f32 v[158:159], v[100:101], v[158:159]
	v_pk_add_f32 v[156:157], v[98:99], v[156:157]
	ds_read_b128 v[98:101], v203 offset:400
	s_waitcnt lgkmcnt(0)
	v_pk_mul_f32 v[100:101], v[158:159], v[100:101]
	v_pk_mul_f32 v[98:99], v[156:157], v[98:99]

; __device__ __forceinline__ unsigned pk2(float lo, float hi) { f32x2 v = {lo, hi}; bf16x2_t b = __builtin_convertvector(v, bf16x2_t); return __builtin_bit_cast(unsigned, b); }
; __device__ __forceinline__ float bflo(unsigned w) { return __uint_as_float(w << 16); }
; __device__ __forceinline__ float bfhi(unsigned w) { return __uint_as_float(w & 0xffff0000u); }
;     __device__ __forceinline__ void operator()(const f32x4 (&acc)[2][2][4][2], const Unit& u, int wr, int wc, int fr, int fq) const {
;     ...
;         for (int j = 0; j < 8; ++j) { const int ai = j >> 2, m = j & 3; const int row = row0 + ai * HALF + m * 16; const size_t off = (size_t)row * DM + col0; float ss = 0.f;
;             if (MODE < 3 && j < 6) ldgrp(nx2, (size_t)(row0 + ((j + 2) >> 2) * HALF + ((j + 2) & 3) * 16) * DM + col0);
; #pragma unroll
;             for (int bj = 0; bj < 2; ++bj) { f32x4 o[2];
; #pragma unroll
;                 for (int n = 0; n < 2; ++n) { const int cc = bj * HALF + 4 * n;
;                     f32x4 v = acc[ai][bj][m][n];
;                     if (bias) { v = (v + *(const f32x4*)(bias + col0 + cc)) * *(const f32x4*)(scale + col0 + cc); }
;                     f32x4 b;
;                     if (MODE >= 3) b = (f32x4){0.f, 0.f, 0.f, 0.f};
;                     else if (MODE == 0) b = __builtin_bit_cast(f32x4, cur[bj][n]);
;                     else { const unsigned w0 = n ? cur[bj][0].z : cur[bj][0].x, w1 = n ? cur[bj][0].w : cur[bj][0].y; b = (f32x4){bflo(w0), bfhi(w0), bflo(w1), bfhi(w1)}; }
;                     o[n] = b + v;
;                     if (MODE == 2 || MODE == 4) *(f32x4*)(out + off + cc) = o[n];
;                     ss += (o[n][0] * o[n][0] + o[n][1] * o[n][1]) + (o[n][2] * o[n][2] + o[n][3] * o[n][3]); }
;                 if (MODE != 2 && MODE != 4) { u32x4 w; w.x = pk2(o[0][0], o[0][1]); w.y = pk2(o[0][2], o[0][3]); w.z = pk2(o[1][0], o[1][1]); w.w = pk2(o[1][2], o[1][3]); *(u32x4*)(xb + off + bj * HALF) = w; } }
;             if (MODE != 2 && MODE != 4 && rsq) { ss += __shfl_xor(ss, 16); ss += __shfl_xor(ss, 32); if (fq == 0) rsq[(size_t)row * 64 + u.pn * 4 + wc] = ss; }
.LBB0_920:
	s_nop 0
	v_add_u32_e32 v146, 0x80, v198
	v_ashrrev_i32_e32 v147, 31, v146
	s_waitcnt lgkmcnt(0)
	v_lshlrev_b64 v[98:99], 13, v[146:147]
	v_lshl_add_u64 v[98:99], s[12:13], 0, v[98:99]
	v_lshl_add_u64 v[102:103], v[192:193], 2, v[98:99]
	global_load_dwordx4 v[106:109], v[102:103], off offset:16
	global_load_dwordx4 v[110:113], v[102:103], off
	global_load_dwordx4 v[98:101], v[102:103], off offset:528
	s_nop 0
	global_load_dwordx4 v[102:105], v[102:103], off offset:512
	s_and_b64 vcc, exec, s[8:9]
	s_cbranch_vccnz .LBB0_922
	ds_read_b128 v[148:151], v203
	s_waitcnt vmcnt(4) lgkmcnt(0)
	v_pk_add_f32 v[150:151], v[94:95], v[150:151]
	v_pk_add_f32 v[148:149], v[92:93], v[148:149]
	ds_read_b128 v[92:95], v203 offset:256
	s_waitcnt lgkmcnt(0)
	v_pk_mul_f32 v[94:95], v[150:151], v[94:95]
	v_pk_mul_f32 v[92:93], v[148:149], v[92:93]
.LBB0_922:
	s_and_b64 vcc, exec, s[8:9]
	s_cbranch_vccnz .LBB0_924
	ds_read_b128 v[148:151], v203 offset:16
	s_waitcnt lgkmcnt(0)
	v_pk_add_f32 v[150:151], v[90:91], v[150:151]
	v_pk_add_f32 v[148:149], v[88:89], v[148:149]
	ds_read_b128 v[88:91], v203 offset:272
	s_waitcnt lgkmcnt(0)
	v_pk_mul_f32 v[90:91], v[150:151], v[90:91]
	v_pk_mul_f32 v[88:89], v[148:149], v[88:89]
.LBB0_924:
	v_pk_add_f32 v[94:95], v[144:145], v[94:95]
	v_lshlrev_b64 v[144:145], 12, v[196:197]
	v_pk_add_f32 v[92:93], v[142:143], v[92:93]
	v_pk_add_f32 v[90:91], v[140:141], v[90:91]
	v_pk_add_f32 v[88:89], v[138:139], v[88:89]
	v_lshl_add_u64 v[138:139], s[62:63], 0, v[144:145]
	v_cvt_pk_bf16_f32 v140, v92, v93
	v_cvt_pk_bf16_f32 v141, v94, v95
	v_cvt_pk_bf16_f32 v142, v88, v89
	v_cvt_pk_bf16_f32 v143, v90, v91
	v_lshl_add_u64 v[138:139], v[192:193], 1, v[138:139]
	s_and_b64 vcc, exec, s[8:9]
	global_store_dwordx4 v[138:139], v[140:143], off
	s_cbranch_vccnz .LBB0_926
	ds_read_b128 v[140:143], v203 offset:128
	s_waitcnt lgkmcnt(0)
	v_pk_add_f32 v[142:143], v[86:87], v[142:143]
	v_pk_add_f32 v[140:141], v[84:85], v[140:141]
	ds_read_b128 v[84:87], v203 offset:384
	s_waitcnt lgkmcnt(0)
	v_pk_mul_f32 v[86:87], v[142:143], v[86:87]
	v_pk_mul_f32 v[84:85], v[140:141], v[84:85]
.LBB0_926:
	s_and_b64 vcc, exec, s[8:9]
	s_cbranch_vccnz .LBB0_928
	ds_read_b128 v[140:143], v203 offset:144
	s_waitcnt lgkmcnt(0)
	v_pk_add_f32 v[142:143], v[82:83], v[142:143]
	v_pk_add_f32 v[140:141], v[80:81], v[140:141]
	ds_read_b128 v[80:83], v203 offset:400
	s_waitcnt lgkmcnt(0)
	v_pk_mul_f32 v[82:83], v[142:143], v[82:83]
	v_pk_mul_f32 v[80:81], v[140:141], v[80:81]

; __device__ __forceinline__ unsigned pk2(float lo, float hi) { f32x2 v = {lo, hi}; bf16x2_t b = __builtin_convertvector(v, bf16x2_t); return __builtin_bit_cast(unsigned, b); }
; __device__ __forceinline__ float bflo(unsigned w) { return __uint_as_float(w << 16); }
; __device__ __forceinline__ float bfhi(unsigned w) { return __uint_as_float(w & 0xffff0000u); }
;     __device__ __forceinline__ void operator()(const f32x4 (&acc)[2][2][4][2], const Unit& u, int wr, int wc, int fr, int fq) const {
;     ...
;         for (int j = 0; j < 8; ++j) { const int ai = j >> 2, m = j & 3; const int row = row0 + ai * HALF + m * 16; const size_t off = (size_t)row * DM + col0; float ss = 0.f;
;             if (MODE < 3 && j < 6) ldgrp(nx2, (size_t)(row0 + ((j + 2) >> 2) * HALF + ((j + 2) & 3) * 16) * DM + col0);
; #pragma unroll
;             for (int bj = 0; bj < 2; ++bj) { f32x4 o[2];
; #pragma unroll
;                 for (int n = 0; n < 2; ++n) { const int cc = bj * HALF + 4 * n;
;                     f32x4 v = acc[ai][bj][m][n];
;                     if (bias) { v = (v + *(const f32x4*)(bias + col0 + cc)) * *(const f32x4*)(scale + col0 + cc); }
;                     f32x4 b;
;                     if (MODE >= 3) b = (f32x4){0.f, 0.f, 0.f, 0.f};
;                     else if (MODE == 0) b = __builtin_bit_cast(f32x4, cur[bj][n]);
;                     else { const unsigned w0 = n ? cur[bj][0].z : cur[bj][0].x, w1 = n ? cur[bj][0].w : cur[bj][0].y; b = (f32x4){bflo(w0), bfhi(w0), bflo(w1), bfhi(w1)}; }
;                     o[n] = b + v;
;                     if (MODE == 2 || MODE == 4) *(f32x4*)(out + off + cc) = o[n];
;                     ss += (o[n][0] * o[n][0] + o[n][1] * o[n][1]) + (o[n][2] * o[n][2] + o[n][3] * o[n][3]); }
;                 if (MODE != 2 && MODE != 4) { u32x4 w; w.x = pk2(o[0][0], o[0][1]); w.y = pk2(o[0][2], o[0][3]); w.z = pk2(o[1][0], o[1][1]); w.w = pk2(o[1][2], o[1][3]); *(u32x4*)(xb + off + bj * HALF) = w; } }
;             if (MODE != 2 && MODE != 4 && rsq) { ss += __shfl_xor(ss, 16); ss += __shfl_xor(ss, 32); if (fq == 0) rsq[(size_t)row * 64 + u.pn * 4 + wc] = ss; }
.LBB0_932:
	s_waitcnt lgkmcnt(0)
	v_lshl_add_u64 v[80:81], v[192:193], 2, v[194:195]
	s_mov_b64 s[16:17], 0x120000
	v_lshl_add_u64 v[84:85], v[80:81], 0, s[16:17]
	v_add_co_u32_e32 v80, vcc, 0x120000, v80
	s_nop 1
	v_addc_co_u32_e32 v81, vcc, 0, v81, vcc
	global_load_dwordx4 v[92:95], v[80:81], off
	s_nop 0
	global_load_dwordx4 v[80:83], v[84:85], off offset:528
	global_load_dwordx4 v[88:91], v[84:85], off offset:16
	s_nop 0
	global_load_dwordx4 v[84:87], v[84:85], off offset:512
	s_and_b64 vcc, exec, s[8:9]
	s_cbranch_vccnz .LBB0_934
	ds_read_b128 v[122:125], v203
	s_waitcnt vmcnt(4) lgkmcnt(0)
	v_pk_add_f32 v[124:125], v[78:79], v[124:125]
	v_pk_add_f32 v[122:123], v[76:77], v[122:123]
	ds_read_b128 v[76:79], v203 offset:256
	s_waitcnt lgkmcnt(0)
	v_pk_mul_f32 v[78:79], v[124:125], v[78:79]
	v_pk_mul_f32 v[76:77], v[122:123], v[76:77]
.LBB0_934:
	s_and_b64 vcc, exec, s[8:9]
	s_cbranch_vccnz .LBB0_936
	ds_read_b128 v[122:125], v203 offset:16
	s_waitcnt lgkmcnt(0)
	v_pk_add_f32 v[124:125], v[74:75], v[124:125]
	v_pk_add_f32 v[122:123], v[72:73], v[122:123]
	ds_read_b128 v[72:75], v203 offset:272
	s_waitcnt lgkmcnt(0)
	v_pk_mul_f32 v[74:75], v[124:125], v[74:75]
	v_pk_mul_f32 v[72:73], v[122:123], v[72:73]
.LBB0_936:
	v_lshlrev_b64 v[122:123], 12, v[162:163]
	s_waitcnt vmcnt(14)
	v_pk_add_f32 v[78:79], v[136:137], v[78:79]
	v_pk_add_f32 v[76:77], v[134:135], v[76:77]
	v_pk_add_f32 v[74:75], v[128:129], v[74:75]
	v_pk_add_f32 v[72:73], v[126:127], v[72:73]
	v_lshl_add_u64 v[122:123], s[62:63], 0, v[122:123]
	v_cvt_pk_bf16_f32 v124, v76, v77
	v_cvt_pk_bf16_f32 v125, v78, v79
	v_cvt_pk_bf16_f32 v126, v72, v73
	v_cvt_pk_bf16_f32 v127, v74, v75
	v_lshl_add_u64 v[122:123], v[192:193], 1, v[122:123]
	s_and_b64 vcc, exec, s[8:9]
	global_store_dwordx4 v[122:123], v[124:127], off
	s_cbranch_vccnz .LBB0_938
	ds_read_b128 v[124:127], v203 offset:128
	s_waitcnt lgkmcnt(0)
	v_pk_add_f32 v[126:127], v[70:71], v[126:127]
	v_pk_add_f32 v[124:125], v[68:69], v[124:125]
	ds_read_b128 v[68:71], v203 offset:384
	s_waitcnt lgkmcnt(0)
	v_pk_mul_f32 v[70:71], v[126:127], v[70:71]
	v_pk_mul_f32 v[68:69], v[124:125], v[68:69]
.LBB0_938:
	s_and_b64 vcc, exec, s[8:9]
	s_cbranch_vccnz .LBB0_940
	ds_read_b128 v[124:127], v203 offset:144
	s_waitcnt lgkmcnt(0)
	v_pk_add_f32 v[126:127], v[66:67], v[126:127]
	v_pk_add_f32 v[124:125], v[64:65], v[124:125]
	ds_read_b128 v[64:67], v203 offset:400
	s_waitcnt lgkmcnt(0)
	v_pk_mul_f32 v[66:67], v[126:127], v[66:67]
	v_pk_mul_f32 v[64:65], v[124:125], v[64:65]

; __device__ __forceinline__ unsigned pk2(float lo, float hi) { f32x2 v = {lo, hi}; bf16x2_t b = __builtin_convertvector(v, bf16x2_t); return __builtin_bit_cast(unsigned, b); }
; __device__ __forceinline__ float bflo(unsigned w) { return __uint_as_float(w << 16); }
; __device__ __forceinline__ float bfhi(unsigned w) { return __uint_as_float(w & 0xffff0000u); }
;     __device__ __forceinline__ void operator()(const f32x4 (&acc)[2][2][4][2], const Unit& u, int wr, int wc, int fr, int fq) const {
;     ...
;         for (int j = 0; j < 8; ++j) { const int ai = j >> 2, m = j & 3; const int row = row0 + ai * HALF + m * 16; const size_t off = (size_t)row * DM + col0; float ss = 0.f;
;             if (MODE < 3 && j < 6) ldgrp(nx2, (size_t)(row0 + ((j + 2) >> 2) * HALF + ((j + 2) & 3) * 16) * DM + col0);
; #pragma unroll
;             for (int bj = 0; bj < 2; ++bj) { f32x4 o[2];
; #pragma unroll
;                 for (int n = 0; n < 2; ++n) { const int cc = bj * HALF + 4 * n;
;                     f32x4 v = acc[ai][bj][m][n];
;                     if (bias) { v = (v + *(const f32x4*)(bias + col0 + cc)) * *(const f32x4*)(scale + col0 + cc); }
;                     f32x4 b;
;                     if (MODE >= 3) b = (f32x4){0.f, 0.f, 0.f, 0.f};
;                     else if (MODE == 0) b = __builtin_bit_cast(f32x4, cur[bj][n]);
;                     else { const unsigned w0 = n ? cur[bj][0].z : cur[bj][0].x, w1 = n ? cur[bj][0].w : cur[bj][0].y; b = (f32x4){bflo(w0), bfhi(w0), bflo(w1), bfhi(w1)}; }
;                     o[n] = b + v;
;                     if (MODE == 2 || MODE == 4) *(f32x4*)(out + off + cc) = o[n];
;                     ss += (o[n][0] * o[n][0] + o[n][1] * o[n][1]) + (o[n][2] * o[n][2] + o[n][3] * o[n][3]); }
;                 if (MODE != 2 && MODE != 4) { u32x4 w; w.x = pk2(o[0][0], o[0][1]); w.y = pk2(o[0][2], o[0][3]); w.z = pk2(o[1][0], o[1][1]); w.w = pk2(o[1][2], o[1][3]); *(u32x4*)(xb + off + bj * HALF) = w; } }
;             if (MODE != 2 && MODE != 4 && rsq) { ss += __shfl_xor(ss, 16); ss += __shfl_xor(ss, 32); if (fq == 0) rsq[(size_t)row * 64 + u.pn * 4 + wc] = ss; }
.LBB0_944:
	s_nop 0
	v_or_b32_e32 v114, 32, v146
	v_ashrrev_i32_e32 v115, 31, v114
	s_waitcnt lgkmcnt(0)
	v_lshlrev_b64 v[64:65], 13, v[114:115]
	v_lshl_add_u64 v[64:65], s[12:13], 0, v[64:65]
	v_lshl_add_u64 v[68:69], v[192:193], 2, v[64:65]
	global_load_dwordx4 v[72:75], v[68:69], off offset:16
	global_load_dwordx4 v[76:79], v[68:69], off
	global_load_dwordx4 v[64:67], v[68:69], off offset:528
	s_nop 0
	global_load_dwordx4 v[68:71], v[68:69], off offset:512
	s_and_b64 vcc, exec, s[8:9]
	s_cbranch_vccnz .LBB0_946
	ds_read_b128 v[116:119], v203
	s_waitcnt vmcnt(4) lgkmcnt(0)
	v_pk_add_f32 v[118:119], v[62:63], v[118:119]
	v_pk_add_f32 v[116:117], v[60:61], v[116:117]
	ds_read_b128 v[60:63], v203 offset:256
	s_waitcnt lgkmcnt(0)
	v_pk_mul_f32 v[62:63], v[118:119], v[62:63]
	v_pk_mul_f32 v[60:61], v[116:117], v[60:61]
.LBB0_946:
	s_and_b64 vcc, exec, s[8:9]
	s_cbranch_vccnz .LBB0_948
	ds_read_b128 v[116:119], v203 offset:16
	s_waitcnt lgkmcnt(0)
	v_pk_add_f32 v[118:119], v[58:59], v[118:119]
	v_pk_add_f32 v[116:117], v[56:57], v[116:117]
	ds_read_b128 v[56:59], v203 offset:272
	s_waitcnt lgkmcnt(0)
	v_pk_mul_f32 v[58:59], v[118:119], v[58:59]
	v_pk_mul_f32 v[56:57], v[116:117], v[56:57]
.LBB0_948:
	s_waitcnt vmcnt(14)
	v_pk_add_f32 v[62:63], v[112:113], v[62:63]
	v_lshlrev_b64 v[112:113], 12, v[146:147]
	v_pk_add_f32 v[60:61], v[110:111], v[60:61]
	v_pk_add_f32 v[58:59], v[108:109], v[58:59]
	v_pk_add_f32 v[56:57], v[106:107], v[56:57]
	v_lshl_add_u64 v[106:107], s[62:63], 0, v[112:113]
	v_cvt_pk_bf16_f32 v108, v60, v61
	v_cvt_pk_bf16_f32 v109, v62, v63
	v_cvt_pk_bf16_f32 v110, v56, v57
	v_cvt_pk_bf16_f32 v111, v58, v59
	v_lshl_add_u64 v[106:107], v[192:193], 1, v[106:107]
	s_and_b64 vcc, exec, s[8:9]
	global_store_dwordx4 v[106:107], v[108:111], off
	s_cbranch_vccnz .LBB0_950
	ds_read_b128 v[108:111], v203 offset:128
	s_waitcnt lgkmcnt(0)
	v_pk_add_f32 v[110:111], v[54:55], v[110:111]
	v_pk_add_f32 v[108:109], v[52:53], v[108:109]
	ds_read_b128 v[52:55], v203 offset:384
	s_waitcnt lgkmcnt(0)
	v_pk_mul_f32 v[54:55], v[110:111], v[54:55]
	v_pk_mul_f32 v[52:53], v[108:109], v[52:53]
.LBB0_950:
	s_and_b64 vcc, exec, s[8:9]
	s_cbranch_vccnz .LBB0_952
	ds_read_b128 v[108:111], v203 offset:144
	s_waitcnt lgkmcnt(0)
	v_pk_add_f32 v[110:111], v[50:51], v[110:111]
	v_pk_add_f32 v[108:109], v[48:49], v[108:109]
	ds_read_b128 v[48:51], v203 offset:400
	s_waitcnt lgkmcnt(0)
	v_pk_mul_f32 v[50:51], v[110:111], v[50:51]
	v_pk_mul_f32 v[48:49], v[108:109], v[48:49]

; __device__ __forceinline__ unsigned pk2(float lo, float hi) { f32x2 v = {lo, hi}; bf16x2_t b = __builtin_convertvector(v, bf16x2_t); return __builtin_bit_cast(unsigned, b); }
; __device__ __forceinline__ float bflo(unsigned w) { return __uint_as_float(w << 16); }
; __device__ __forceinline__ float bfhi(unsigned w) { return __uint_as_float(w & 0xffff0000u); }
;     __device__ __forceinline__ void operator()(const f32x4 (&acc)[2][2][4][2], const Unit& u, int wr, int wc, int fr, int fq) const {
;     ...
;         for (int j = 0; j < 8; ++j) { const int ai = j >> 2, m = j & 3; const int row = row0 + ai * HALF + m * 16; const size_t off = (size_t)row * DM + col0; float ss = 0.f;
;             if (MODE < 3 && j < 6) ldgrp(nx2, (size_t)(row0 + ((j + 2) >> 2) * HALF + ((j + 2) & 3) * 16) * DM + col0);
; #pragma unroll
;             for (int bj = 0; bj < 2; ++bj) { f32x4 o[2];
; #pragma unroll
;                 for (int n = 0; n < 2; ++n) { const int cc = bj * HALF + 4 * n;
;                     f32x4 v = acc[ai][bj][m][n];
;                     if (bias) { v = (v + *(const f32x4*)(bias + col0 + cc)) * *(const f32x4*)(scale + col0 + cc); }
;                     f32x4 b;
;                     if (MODE >= 3) b = (f32x4){0.f, 0.f, 0.f, 0.f};
;                     else if (MODE == 0) b = __builtin_bit_cast(f32x4, cur[bj][n]);
;                     else { const unsigned w0 = n ? cur[bj][0].z : cur[bj][0].x, w1 = n ? cur[bj][0].w : cur[bj][0].y; b = (f32x4){bflo(w0), bfhi(w0), bflo(w1), bfhi(w1)}; }
;                     o[n] = b + v;
;                     if (MODE == 2 || MODE == 4) *(f32x4*)(out + off + cc) = o[n];
;                     ss += (o[n][0] * o[n][0] + o[n][1] * o[n][1]) + (o[n][2] * o[n][2] + o[n][3] * o[n][3]); }
;                 if (MODE != 2 && MODE != 4) { u32x4 w; w.x = pk2(o[0][0], o[0][1]); w.y = pk2(o[0][2], o[0][3]); w.z = pk2(o[1][0], o[1][1]); w.w = pk2(o[1][2], o[1][3]); *(u32x4*)(xb + off + bj * HALF) = w; } }
.LBB0_956:
	s_nop 0
	v_or_b32_e32 v98, 48, v146
	v_ashrrev_i32_e32 v99, 31, v98
	s_waitcnt lgkmcnt(0)
	v_lshlrev_b64 v[48:49], 13, v[98:99]
	v_lshl_add_u64 v[48:49], s[12:13], 0, v[48:49]
	v_lshl_add_u64 v[52:53], v[192:193], 2, v[48:49]
	global_load_dwordx4 v[56:59], v[52:53], off offset:16
	global_load_dwordx4 v[60:63], v[52:53], off
	global_load_dwordx4 v[48:51], v[52:53], off offset:528
	s_nop 0
	global_load_dwordx4 v[52:55], v[52:53], off offset:512
	s_and_b64 vcc, exec, s[8:9]
	s_cbranch_vccnz .LBB0_958
	ds_read_b128 v[100:103], v203
	s_waitcnt vmcnt(4) lgkmcnt(0)
	v_pk_add_f32 v[102:103], v[46:47], v[102:103]
	v_pk_add_f32 v[100:101], v[44:45], v[100:101]
	ds_read_b128 v[44:47], v203 offset:256
	s_waitcnt lgkmcnt(0)
	v_pk_mul_f32 v[46:47], v[102:103], v[46:47]
	v_pk_mul_f32 v[44:45], v[100:101], v[44:45]
.LBB0_958:
	s_and_b64 vcc, exec, s[8:9]
	s_cbranch_vccnz .LBB0_960
	ds_read_b128 v[100:103], v203 offset:16
	s_waitcnt lgkmcnt(0)
	v_pk_add_f32 v[102:103], v[42:43], v[102:103]
	v_pk_add_f32 v[100:101], v[40:41], v[100:101]
	ds_read_b128 v[40:43], v203 offset:272
	s_waitcnt lgkmcnt(0)
	v_pk_mul_f32 v[42:43], v[102:103], v[42:43]
	v_pk_mul_f32 v[40:41], v[100:101], v[40:41]
.LBB0_960:
	s_waitcnt vmcnt(15)
	v_pk_add_f32 v[92:93], v[92:93], v[44:45]
	v_or_b32_e32 v44, 16, v146
	v_ashrrev_i32_e32 v45, 31, v44
	v_pk_add_f32 v[46:47], v[94:95], v[46:47]
	v_lshlrev_b64 v[94:95], 12, v[44:45]
	s_waitcnt vmcnt(13)
	v_pk_add_f32 v[42:43], v[90:91], v[42:43]
	v_pk_add_f32 v[40:41], v[88:89], v[40:41]
	v_lshl_add_u64 v[88:89], s[62:63], 0, v[94:95]
	v_cvt_pk_bf16_f32 v100, v92, v93
	v_cvt_pk_bf16_f32 v101, v46, v47
	v_cvt_pk_bf16_f32 v102, v40, v41
	v_cvt_pk_bf16_f32 v103, v42, v43
	v_lshl_add_u64 v[88:89], v[192:193], 1, v[88:89]
	s_and_b64 vcc, exec, s[8:9]
	global_store_dwordx4 v[88:89], v[100:103], off
	s_cbranch_vccnz .LBB0_962
	ds_read_b128 v[100:103], v203 offset:128
	s_waitcnt lgkmcnt(0)
	v_pk_add_f32 v[90:91], v[38:39], v[102:103]
	v_pk_add_f32 v[94:95], v[36:37], v[100:101]
	ds_read_b128 v[36:39], v203 offset:384
	s_waitcnt lgkmcnt(0)
	v_pk_mul_f32 v[38:39], v[90:91], v[38:39]
	v_pk_mul_f32 v[36:37], v[94:95], v[36:37]
.LBB0_962:
	s_and_b64 vcc, exec, s[8:9]
	s_cbranch_vccnz .LBB0_964
	ds_read_b128 v[100:103], v203 offset:144
	s_waitcnt lgkmcnt(0)
	v_pk_add_f32 v[90:91], v[34:35], v[102:103]
	v_pk_add_f32 v[94:95], v[32:33], v[100:101]
	ds_read_b128 v[32:35], v203 offset:400
	s_waitcnt lgkmcnt(0)
	v_pk_mul_f32 v[34:35], v[90:91], v[34:35]
	v_pk_mul_f32 v[32:33], v[94:95], v[32:33]

; __device__ __forceinline__ unsigned pk2(float lo, float hi) { f32x2 v = {lo, hi}; bf16x2_t b = __builtin_convertvector(v, bf16x2_t); return __builtin_bit_cast(unsigned, b); }
; __device__ __forceinline__ float bflo(unsigned w) { return __uint_as_float(w << 16); }
; __device__ __forceinline__ float bfhi(unsigned w) { return __uint_as_float(w & 0xffff0000u); }
;     __device__ __forceinline__ void operator()(const f32x4 (&acc)[2][2][4][2], const Unit& u, int wr, int wc, int fr, int fq) const {
;     ...
;         for (int j = 0; j < 8; ++j) { const int ai = j >> 2, m = j & 3; const int row = row0 + ai * HALF + m * 16; const size_t off = (size_t)row * DM + col0; float ss = 0.f;
;             if (MODE < 3 && j < 6) ldgrp(nx2, (size_t)(row0 + ((j + 2) >> 2) * HALF + ((j + 2) & 3) * 16) * DM + col0);
; #pragma unroll
;             for (int bj = 0; bj < 2; ++bj) { f32x4 o[2];
; #pragma unroll
;                 for (int n = 0; n < 2; ++n) { const int cc = bj * HALF + 4 * n;
;                     f32x4 v = acc[ai][bj][m][n];
;                     if (bias) { v = (v + *(const f32x4*)(bias + col0 + cc)) * *(const f32x4*)(scale + col0 + cc); }
;                     f32x4 b;
;                     if (MODE >= 3) b = (f32x4){0.f, 0.f, 0.f, 0.f};
;                     else if (MODE == 0) b = __builtin_bit_cast(f32x4, cur[bj][n]);
;                     else { const unsigned w0 = n ? cur[bj][0].z : cur[bj][0].x, w1 = n ? cur[bj][0].w : cur[bj][0].y; b = (f32x4){bflo(w0), bfhi(w0), bflo(w1), bfhi(w1)}; }
;                     o[n] = b + v;
;                     if (MODE == 2 || MODE == 4) *(f32x4*)(out + off + cc) = o[n];
;                     ss += (o[n][0] * o[n][0] + o[n][1] * o[n][1]) + (o[n][2] * o[n][2] + o[n][3] * o[n][3]); }
;                 if (MODE != 2 && MODE != 4) { u32x4 w; w.x = pk2(o[0][0], o[0][1]); w.y = pk2(o[0][2], o[0][3]); w.z = pk2(o[1][0], o[1][1]); w.w = pk2(o[1][2], o[1][3]); *(u32x4*)(xb + off + bj * HALF) = w; } }
.LBB0_972:
	s_waitcnt lgkmcnt(0)
	v_lshlrev_b64 v[32:33], 12, v[114:115]
	s_waitcnt vmcnt(10)
	v_pk_add_f32 v[30:31], v[78:79], v[30:31]
	v_pk_add_f32 v[28:29], v[76:77], v[28:29]
	v_pk_add_f32 v[26:27], v[74:75], v[26:27]
	v_pk_add_f32 v[24:25], v[72:73], v[24:25]
	v_lshl_add_u64 v[32:33], s[62:63], 0, v[32:33]
	v_cvt_pk_bf16_f32 v34, v28, v29
	v_cvt_pk_bf16_f32 v35, v30, v31
	v_cvt_pk_bf16_f32 v36, v24, v25
	v_cvt_pk_bf16_f32 v37, v26, v27
	v_lshl_add_u64 v[32:33], v[192:193], 1, v[32:33]
	s_and_b64 vcc, exec, s[8:9]
	global_store_dwordx4 v[32:33], v[34:37], off
	s_cbranch_vccnz .LBB0_974
	ds_read_b128 v[34:37], v203 offset:128
	s_waitcnt lgkmcnt(0)
	v_pk_add_f32 v[36:37], v[22:23], v[36:37]
	v_pk_add_f32 v[34:35], v[20:21], v[34:35]
	ds_read_b128 v[20:23], v203 offset:384
	s_waitcnt lgkmcnt(0)
	v_pk_mul_f32 v[22:23], v[36:37], v[22:23]
	v_pk_mul_f32 v[20:21], v[34:35], v[20:21]
.LBB0_974:
	s_and_b64 vcc, exec, s[8:9]
	s_cbranch_vccnz .LBB0_976
	ds_read_b128 v[34:37], v203 offset:144
	s_waitcnt lgkmcnt(0)
	v_pk_add_f32 v[36:37], v[18:19], v[36:37]
	v_pk_add_f32 v[34:35], v[16:17], v[34:35]
	ds_read_b128 v[16:19], v203 offset:400
	s_waitcnt lgkmcnt(0)
	v_pk_mul_f32 v[18:19], v[36:37], v[18:19]
	v_pk_mul_f32 v[16:17], v[34:35], v[16:17]

; __device__ __forceinline__ unsigned pk2(float lo, float hi) { f32x2 v = {lo, hi}; bf16x2_t b = __builtin_convertvector(v, bf16x2_t); return __builtin_bit_cast(unsigned, b); }
; __device__ __forceinline__ float bflo(unsigned w) { return __uint_as_float(w << 16); }
; __device__ __forceinline__ float bfhi(unsigned w) { return __uint_as_float(w & 0xffff0000u); }
;     __device__ __forceinline__ void operator()(const f32x4 (&acc)[2][2][4][2], const Unit& u, int wr, int wc, int fr, int fq) const {
;     ...
;         for (int j = 0; j < 8; ++j) { const int ai = j >> 2, m = j & 3; const int row = row0 + ai * HALF + m * 16; const size_t off = (size_t)row * DM + col0; float ss = 0.f;
;             if (MODE < 3 && j < 6) ldgrp(nx2, (size_t)(row0 + ((j + 2) >> 2) * HALF + ((j + 2) & 3) * 16) * DM + col0);
; #pragma unroll
;             for (int bj = 0; bj < 2; ++bj) { f32x4 o[2];
; #pragma unroll
;                 for (int n = 0; n < 2; ++n) { const int cc = bj * HALF + 4 * n;
;                     f32x4 v = acc[ai][bj][m][n];
;                     if (bias) { v = (v + *(const f32x4*)(bias + col0 + cc)) * *(const f32x4*)(scale + col0 + cc); }
;                     f32x4 b;
;                     if (MODE >= 3) b = (f32x4){0.f, 0.f, 0.f, 0.f};
;                     else if (MODE == 0) b = __builtin_bit_cast(f32x4, cur[bj][n]);
;                     else { const unsigned w0 = n ? cur[bj][0].z : cur[bj][0].x, w1 = n ? cur[bj][0].w : cur[bj][0].y; b = (f32x4){bflo(w0), bfhi(w0), bflo(w1), bfhi(w1)}; }
;                     o[n] = b + v;
;                     if (MODE == 2 || MODE == 4) *(f32x4*)(out + off + cc) = o[n];
;                     ss += (o[n][0] * o[n][0] + o[n][1] * o[n][1]) + (o[n][2] * o[n][2] + o[n][3] * o[n][3]); }
;                 if (MODE != 2 && MODE != 4) { u32x4 w; w.x = pk2(o[0][0], o[0][1]); w.y = pk2(o[0][2], o[0][3]); w.z = pk2(o[1][0], o[1][1]); w.w = pk2(o[1][2], o[1][3]); *(u32x4*)(xb + off + bj * HALF) = w; } }
.LBB0_984:
	s_waitcnt lgkmcnt(0)
	v_lshlrev_b64 v[16:17], 12, v[98:99]
	s_waitcnt vmcnt(6)
	v_pk_add_f32 v[14:15], v[62:63], v[14:15]
	v_pk_add_f32 v[12:13], v[60:61], v[12:13]
	v_pk_add_f32 v[10:11], v[58:59], v[10:11]
	v_pk_add_f32 v[8:9], v[56:57], v[8:9]
	v_lshl_add_u64 v[16:17], s[62:63], 0, v[16:17]
	v_cvt_pk_bf16_f32 v18, v12, v13
	v_cvt_pk_bf16_f32 v19, v14, v15
	v_cvt_pk_bf16_f32 v20, v8, v9
	v_cvt_pk_bf16_f32 v21, v10, v11
	v_lshl_add_u64 v[16:17], v[192:193], 1, v[16:17]
	s_and_b64 vcc, exec, s[8:9]
	global_store_dwordx4 v[16:17], v[18:21], off
	s_cbranch_vccnz .LBB0_986
	ds_read_b128 v[18:21], v203 offset:128
	s_waitcnt lgkmcnt(0)
	v_pk_add_f32 v[20:21], v[6:7], v[20:21]
	v_pk_add_f32 v[18:19], v[4:5], v[18:19]
	ds_read_b128 v[4:7], v203 offset:384
	s_waitcnt lgkmcnt(0)
	v_pk_mul_f32 v[6:7], v[20:21], v[6:7]
	v_pk_mul_f32 v[4:5], v[18:19], v[4:5]
.LBB0_986:
	s_and_b64 vcc, exec, s[8:9]
	s_cbranch_vccnz .LBB0_988
	ds_read_b128 v[18:21], v203 offset:144
	s_waitcnt lgkmcnt(0)
	v_pk_add_f32 v[20:21], v[2:3], v[20:21]
	v_pk_add_f32 v[18:19], v[0:1], v[18:19]
	ds_read_b128 v[0:3], v203 offset:400
	s_waitcnt lgkmcnt(0)
	v_pk_mul_f32 v[2:3], v[20:21], v[2:3]
	v_pk_mul_f32 v[0:1], v[18:19], v[0:1]
